# write-through (sc1) on the attention / stage3 y stores
# speedup vs baseline: 1.0009x; 1.0009x over previous
; #define LAS __attribute__((address_space(3)))
; template <int D, int QT0>
; __device__ __forceinline__ void qk_tile(const LAS unsigned char* Ks, int KP, const bf16x8 (&qf)[2][D / 32], f32x4 (&s)[4][2], int fr, int fq, float b0, float b1) {
; #pragma unroll
;     for (int a = 0; a < 4; ++a) { s[a][0] = (f32x4){b0, b0, b0, b0}; s[a][1] = (f32x4){b1, b1, b1, b1}; }
; #pragma unroll
;     for (int a = 0; a < 4; ++a)
; #pragma unroll
;         for (int ks = 0; ks < D / 32; ++ks) { const bf16x8 kfr = *(const LAS bf16x8*)(Ks + (a * 16 + fr) * KP + (ks * 32 + fq * 8) * 2);
;             if (QT0 == 0) s[a][0] = MFMA16(kfr, qf[0][ks], s[a][0]);
;             s[a][1] = MFMA16(kfr, qf[1][ks], s[a][1]); }
; }
; template <int D, bool DIAG, int QT0>
; __device__ __forceinline__ void sm_pv_tile(f32x4 (&s)[4][2], const LAS unsigned char* Vs, int VP, f32x4 (&o)[D / 16][2], f32x4 (&ol)[2], int fr, int fq, int keyl0, int qla, int qlb) {
; #pragma unroll
;     for (int qt = QT0; qt < 2; ++qt) {
;         if (DIAG) {
;             const int ql = (qt == 0 ? qla : qlb) + fr - keyl0 - fq * 4;
; #pragma unroll
;             for (int a = 0; a < 4; ++a)
; #pragma unroll
;                 for (int jj = 0; jj < 4; ++jj) s[a][qt][jj] = (a * 16 + jj > ql) ? -1e30f : s[a][qt][jj];
;         }
; #pragma unroll
;         for (int a = 0; a < 4; ++a)
; #pragma unroll
;             for (int jj = 0; jj < 4; ++jj) s[a][qt][jj] = ex2(s[a][qt][jj]);
;     }
; #pragma unroll
;     for (int kst = 0; kst < 2; ++kst) {
;         bf16x8 pb[2];
; #pragma unroll
;         for (int qt = QT0; qt < 2; ++qt) { u32x4 pw; pw.x = pk2(s[2 * kst][qt][0], s[2 * kst][qt][1]); pw.y = pk2(s[2 * kst][qt][2], s[2 * kst][qt][3]);
;             pw.z = pk2(s[2 * kst + 1][qt][0], s[2 * kst + 1][qt][1]); pw.w = pk2(s[2 * kst + 1][qt][2], s[2 * kst + 1][qt][3]); pb[qt] = __builtin_bit_cast(bf16x8, pw); }
;         if (QT0 == 0) ol[0] = MFMA16(ONES8, pb[0], ol[0]);
;         ol[1] = MFMA16(ONES8, pb[1], ol[1]);
; #pragma unroll
; __device__ __forceinline__ void mem_unit(const Args& a, int l, LAS unsigned char* lds, int b, int hm, int qb) {
;     ...
;     for (int kt = 0; kt < 4; ++kt) {
;         if (kt < 3) MEM_LOAD(kt + 1);
;         attn_tile<128, false, 0>(Ks + (kt & 1) * 35840, 272, Vs + (kt & 1) * 35840, 288, qf, o, ol, fr, fq, 0, 0, 0, -gm, -gm);
;         if (kt < 3) MEM_STORE((kt + 1) & 1);
;         BAR_LDS();
;     }
.LBB0_520:
	v_lshl_add_u64 v[116:117], v[166:167], 0, s[46:47]
	v_add_co_u32_e32 v116, vcc, s34, v116
	s_bitcmp1_b32 s6, 0
	s_nop 0
	v_addc_co_u32_e32 v117, vcc, 0, v117, vcc
	global_load_dwordx4 v[128:131], v[116:117], off
	global_load_dwordx4 v[124:127], v[116:117], off offset:1024
	v_lshl_add_u64 v[116:117], v[164:165], 0, s[46:47]
	v_add_co_u32_e32 v116, vcc, s34, v116
	s_cselect_b32 s4, 0x8c00, 0
	s_nop 0
	v_addc_co_u32_e32 v117, vcc, 0, v117, vcc
	v_add_u32_e32 v181, s4, v176
	global_load_dwordx4 v[120:123], v[116:117], off
	s_nop 0
	global_load_dwordx4 v[116:119], v[116:117], off offset:1024
	ds_read_b128 v[132:135], v181
	ds_read_b128 v[140:143], v181 offset:64
	s_waitcnt lgkmcnt(1)
	v_mfma_f32_16x16x32_bf16 v[136:139], v[132:135], v[16:19], v[72:75]
	ds_read_b128 v[204:207], v181 offset:4416
	s_mov_b32 s70, s68
	s_mov_b32 s71, s68
	v_mfma_f32_16x16x32_bf16 v[132:135], v[132:135], v[24:27], v[72:75]
	ds_read_b128 v[212:215], v181 offset:8768
	s_mov_b32 s69, s68
	ds_read_b128 v[220:223], v181 offset:13120
	s_waitcnt lgkmcnt(3)
	v_mfma_f32_16x16x32_bf16 v[136:139], v[140:143], v[20:23], v[136:139]
	v_mfma_f32_16x16x32_bf16 v[132:135], v[140:143], v[28:31], v[132:135]
	ds_read_b128 v[140:143], v181 offset:128
	s_waitcnt lgkmcnt(0)
	v_mfma_f32_16x16x32_bf16 v[136:139], v[140:143], v[12:15], v[136:139]
	v_mfma_f32_16x16x32_bf16 v[132:135], v[140:143], v[36:39], v[132:135]
	ds_read_b128 v[140:143], v181 offset:192
	s_waitcnt lgkmcnt(0)
	v_mfma_f32_16x16x32_bf16 v[136:139], v[140:143], v[8:11], v[136:139]
	s_nop 7
	v_exp_f32_e32 v136, v136
	v_mfma_f32_16x16x32_bf16 v[132:135], v[140:143], v[32:35], v[132:135]
	ds_read_b128 v[140:143], v181 offset:4352
	v_exp_f32_e32 v137, v137
	v_exp_f32_e32 v138, v138
	s_waitcnt lgkmcnt(0)
	v_mfma_f32_16x16x32_bf16 v[200:203], v[140:143], v[16:19], v[72:75]
	v_exp_f32_e32 v139, v139
	v_mfma_f32_16x16x32_bf16 v[140:143], v[140:143], v[24:27], v[72:75]
	v_mfma_f32_16x16x32_bf16 v[200:203], v[204:207], v[20:23], v[200:203]
	v_mfma_f32_16x16x32_bf16 v[140:143], v[204:207], v[28:31], v[140:143]
	ds_read_b128 v[204:207], v181 offset:4480
	s_waitcnt lgkmcnt(0)
	v_mfma_f32_16x16x32_bf16 v[200:203], v[204:207], v[12:15], v[200:203]
	v_mfma_f32_16x16x32_bf16 v[140:143], v[204:207], v[36:39], v[140:143]
	ds_read_b128 v[204:207], v181 offset:4544
	s_waitcnt lgkmcnt(0)
	v_mfma_f32_16x16x32_bf16 v[200:203], v[204:207], v[8:11], v[200:203]
	s_nop 7
	v_exp_f32_e32 v225, v201
	v_mfma_f32_16x16x32_bf16 v[140:143], v[204:207], v[32:35], v[140:143]
	ds_read_b128 v[204:207], v181 offset:8704
	v_exp_f32_e32 v226, v202
	v_exp_f32_e32 v227, v203
	s_waitcnt lgkmcnt(0)
	v_mfma_f32_16x16x32_bf16 v[208:211], v[204:207], v[16:19], v[72:75]
	v_exp_f32_e32 v224, v200
	s_nop 1
	v_exp_f32_e32 v140, v140
	v_exp_f32_e32 v141, v141
	v_mfma_f32_16x16x32_bf16 v[204:207], v[204:207], v[24:27], v[72:75]
	v_exp_f32_e32 v142, v142
	v_exp_f32_e32 v143, v143
	v_mfma_f32_16x16x32_bf16 v[208:211], v[212:215], v[20:23], v[208:211]
	v_mfma_f32_16x16x32_bf16 v[204:207], v[212:215], v[28:31], v[204:207]
	ds_read_b128 v[212:215], v181 offset:8832
	s_waitcnt lgkmcnt(0)
	v_mfma_f32_16x16x32_bf16 v[208:211], v[212:215], v[12:15], v[208:211]
	v_mfma_f32_16x16x32_bf16 v[204:207], v[212:215], v[36:39], v[204:207]
	ds_read_b128 v[212:215], v181 offset:8896
	s_waitcnt lgkmcnt(0)
	v_mfma_f32_16x16x32_bf16 v[208:211], v[212:215], v[8:11], v[208:211]
	s_nop 7
	v_exp_f32_e32 v200, v211
	v_mfma_f32_16x16x32_bf16 v[212:215], v[212:215], v[32:35], v[204:207]
	v_exp_f32_e32 v182, v209
	v_exp_f32_e32 v183, v210
	s_nop 0
	ds_read_b128 v[204:207], v181 offset:13056
	s_waitcnt lgkmcnt(0)
	v_mfma_f32_16x16x32_bf16 v[216:219], v[204:207], v[16:19], v[72:75]
	v_mfma_f32_16x16x32_bf16 v[204:207], v[204:207], v[24:27], v[72:75]
	v_mfma_f32_16x16x32_bf16 v[216:219], v[220:223], v[20:23], v[216:219]
	v_mfma_f32_16x16x32_bf16 v[204:207], v[220:223], v[28:31], v[204:207]
	ds_read_b128 v[220:223], v181 offset:13184
	s_waitcnt lgkmcnt(0)
	v_mfma_f32_16x16x32_bf16 v[216:219], v[220:223], v[12:15], v[216:219]
	v_mfma_f32_16x16x32_bf16 v[204:207], v[220:223], v[36:39], v[204:207]
	ds_read_b128 v[220:223], v181 offset:13248
	v_exp_f32_e32 v181, v208
	v_exp_f32_e32 v208, v215
	s_waitcnt lgkmcnt(0)
	v_mfma_f32_16x16x32_bf16 v[216:219], v[220:223], v[8:11], v[216:219]
	s_nop 7
	v_exp_f32_e32 v201, v216
	v_mfma_f32_16x16x32_bf16 v[220:223], v[220:223], v[32:35], v[204:207]
	v_exp_f32_e32 v202, v217
	v_exp_f32_e32 v203, v218
	v_exp_f32_e32 v216, v132
	v_exp_f32_e32 v204, v219
	v_exp_f32_e32 v217, v133
	v_exp_f32_e32 v218, v134
	v_exp_f32_e32 v219, v135
	v_exp_f32_e32 v206, v213
	v_add_u32_e32 v213, s4, v172
	v_exp_f32_e32 v211, v222
	v_add_u32_e32 v222, v213, v170
	v_exp_f32_e32 v207, v214
	v_exp_f32_e32 v209, v220
	v_exp_f32_e32 v210, v221
	v_cvt_pk_bf16_f32 v132, v136, v137
	v_cvt_pk_bf16_f32 v136, v216, v217
	v_cvt_pk_bf16_f32 v137, v218, v219
	ds_read_b64_tr_b16 v[216:217], v222 offset:22016
	ds_read_b64_tr_b16 v[214:215], v222 offset:17408
	ds_read_b64_tr_b16 v[218:219], v222 offset:17440
	ds_read_b64_tr_b16 v[220:221], v222 offset:22048
	v_cvt_pk_bf16_f32 v133, v138, v139
	v_cvt_pk_bf16_f32 v134, v224, v225
	v_cvt_pk_bf16_f32 v135, v226, v227
	v_cvt_pk_bf16_f32 v138, v140, v141
	v_cvt_pk_bf16_f32 v139, v142, v143
	s_waitcnt lgkmcnt(2)
	v_mfma_f32_16x16x32_bf16 v[84:87], v[214:217], v[132:135], v[84:87]
	v_mov_b64_e32 v[142:143], s[70:71]
	v_mov_b64_e32 v[140:141], s[68:69]
	v_exp_f32_e32 v205, v212
	v_mfma_f32_16x16x32_bf16 v[88:91], v[214:217], v[136:139], v[88:91]
	ds_read_b64_tr_b16 v[214:215], v222 offset:17472
	ds_read_b64_tr_b16 v[216:217], v222 offset:22080
	v_exp_f32_e32 v212, v223
	s_andn2_b32 s4, 1, s6
	s_waitcnt lgkmcnt(2)
; __device__ __forceinline__ unsigned pk2(float lo, float hi) { f32x2_t v = {lo, hi}; bf16x2_t b = __builtin_convertvector(v, bf16x2_t); return __builtin_bit_cast(unsigned, b); }
; #define MFMA16(a, b, c) __builtin_amdgcn_mfma_f32_16x16x32_bf16((a), (b), (c), 0, 0, 0)
; template <int D, bool DIAG, int QT0>
; __device__ __forceinline__ void sm_pv_tile(f32x4 (&s)[4][2], const LAS unsigned char* Vs, int VP, f32x4 (&o)[D / 16][2], f32x4 (&ol)[2], int fr, int fq, int keyl0, int qla, int qlb) {
;     ...
;     for (int kst = 0; kst < 2; ++kst) {
;         bf16x8 pb[2];
; #pragma unroll
;         for (int qt = QT0; qt < 2; ++qt) { u32x4 pw; pw.x = pk2(s[2 * kst][qt][0], s[2 * kst][qt][1]); pw.y = pk2(s[2 * kst][qt][2], s[2 * kst][qt][3]);
;             pw.z = pk2(s[2 * kst + 1][qt][0], s[2 * kst + 1][qt][1]); pw.w = pk2(s[2 * kst + 1][qt][2], s[2 * kst + 1][qt][3]); pb[qt] = __builtin_bit_cast(bf16x8, pw); }
;         if (QT0 == 0) ol[0] = MFMA16(ONES8, pb[0], ol[0]);
;         ol[1] = MFMA16(ONES8, pb[1], ol[1]);
; #pragma unroll
;         for (int dt = 0; dt < D / 16; ++dt) { const s16x4 lo = tr4(Vs, VP, kst * 32 + fq * 4, dt * 16, fr), hi = tr4(Vs, VP, kst * 32 + 16 + fq * 4, dt * 16, fr);
;             const bf16x8 vf = __builtin_shufflevector(lo, hi, 0, 1, 2, 3, 4, 5, 6, 7);
;             if (QT0 == 0) o[dt][0] = MFMA16(vf, pb[0], o[dt][0]);
;             o[dt][1] = MFMA16(vf, pb[1], o[dt][1]); }
;     }
	v_mfma_f32_16x16x32_bf16 v[92:95], v[218:221], v[132:135], v[92:95]
	s_mul_i32 s4, s4, 0x8c00
	s_add_i32 s6, s6, 1
	s_add_u32 s46, s46, 0x20000
	v_mfma_f32_16x16x32_bf16 v[96:99], v[218:221], v[136:139], v[96:99]
	v_add_u32_e32 v218, v213, v169
	v_add_u32_e32 v213, v213, v168
	s_addc_u32 s47, s47, 0
	s_waitcnt lgkmcnt(0)
	v_mfma_f32_16x16x32_bf16 v[76:79], v[214:217], v[132:135], v[76:79]
	s_cmp_lg_u32 s46, 0x60000
	v_mfma_f32_16x16x32_bf16 v[80:83], v[214:217], v[136:139], v[80:83]
	ds_read_b64_tr_b16 v[214:215], v218 offset:17408
	ds_read_b64_tr_b16 v[216:217], v218 offset:22016
	s_waitcnt lgkmcnt(0)
	v_mfma_f32_16x16x32_bf16 v[100:103], v[214:217], v[132:135], v[100:103]
	v_mfma_f32_16x16x32_bf16 v[104:107], v[214:217], v[136:139], v[104:107]
	ds_read_b64_tr_b16 v[214:215], v222 offset:17536
	ds_read_b64_tr_b16 v[216:217], v222 offset:22144
	s_waitcnt lgkmcnt(0)
	v_mfma_f32_16x16x32_bf16 v[64:67], v[214:217], v[132:135], v[64:67]
	v_mfma_f32_16x16x32_bf16 v[68:71], v[214:217], v[136:139], v[68:71]
	ds_read_b64_tr_b16 v[214:215], v222 offset:17568
	ds_read_b64_tr_b16 v[216:217], v222 offset:22176
	s_waitcnt lgkmcnt(0)
	v_mfma_f32_16x16x32_bf16 v[56:59], v[214:217], v[132:135], v[56:59]
	v_mfma_f32_16x16x32_bf16 v[60:63], v[214:217], v[136:139], v[60:63]
	ds_read_b64_tr_b16 v[214:215], v222 offset:17600
	ds_read_b64_tr_b16 v[216:217], v222 offset:22208
	s_waitcnt lgkmcnt(0)
	v_mfma_f32_16x16x32_bf16 v[48:51], v[214:217], v[132:135], v[48:51]
	v_mfma_f32_16x16x32_bf16 v[52:55], v[214:217], v[136:139], v[52:55]
	ds_read_b64_tr_b16 v[214:215], v213 offset:17408
	ds_read_b64_tr_b16 v[216:217], v213 offset:22016
	v_mfma_f32_16x16x32_bf16 v[108:111], v[140:143], v[132:135], v[108:111]
	v_mfma_f32_16x16x32_bf16 v[112:115], v[140:143], v[136:139], v[112:115]
	s_waitcnt lgkmcnt(0)
	v_mfma_f32_16x16x32_bf16 v[40:43], v[214:217], v[132:135], v[40:43]
	v_cvt_pk_bf16_f32 v132, v181, v182
	v_cvt_pk_bf16_f32 v133, v183, v200
	v_cvt_pk_bf16_f32 v134, v201, v202
	v_mfma_f32_16x16x32_bf16 v[44:47], v[214:217], v[136:139], v[44:47]
	v_cvt_pk_bf16_f32 v135, v203, v204
	v_cvt_pk_bf16_f32 v136, v205, v206
	v_cvt_pk_bf16_f32 v137, v207, v208
	v_cvt_pk_bf16_f32 v138, v209, v210
	v_cvt_pk_bf16_f32 v139, v211, v212
	v_mfma_f32_16x16x32_bf16 v[108:111], v[140:143], v[132:135], v[108:111]
	v_add_u32_e32 v181, s4, v173
	v_mfma_f32_16x16x32_bf16 v[112:115], v[140:143], v[136:139], v[112:115]
	ds_read_b64_tr_b16 v[140:141], v222 offset:26624
	ds_read_b64_tr_b16 v[142:143], v222 offset:31232
	s_waitcnt lgkmcnt(0)
	v_mfma_f32_16x16x32_bf16 v[84:87], v[140:143], v[132:135], v[84:87]
	v_mfma_f32_16x16x32_bf16 v[88:91], v[140:143], v[136:139], v[88:91]
	ds_read_b64_tr_b16 v[140:141], v222 offset:26656
	ds_read_b64_tr_b16 v[142:143], v222 offset:31264
	s_waitcnt lgkmcnt(0)
	v_mfma_f32_16x16x32_bf16 v[92:95], v[140:143], v[132:135], v[92:95]
	v_mfma_f32_16x16x32_bf16 v[96:99], v[140:143], v[136:139], v[96:99]
	ds_read_b64_tr_b16 v[140:141], v222 offset:26688
	ds_read_b64_tr_b16 v[142:143], v222 offset:31296
	s_waitcnt lgkmcnt(0)
	v_mfma_f32_16x16x32_bf16 v[76:79], v[140:143], v[132:135], v[76:79]
	v_mfma_f32_16x16x32_bf16 v[80:83], v[140:143], v[136:139], v[80:83]
	ds_read_b64_tr_b16 v[140:141], v218 offset:26624
	ds_read_b64_tr_b16 v[142:143], v218 offset:31232
	s_waitcnt lgkmcnt(0)
	v_mfma_f32_16x16x32_bf16 v[100:103], v[140:143], v[132:135], v[100:103]
	v_mfma_f32_16x16x32_bf16 v[104:107], v[140:143], v[136:139], v[104:107]
	ds_read_b64_tr_b16 v[140:141], v222 offset:26752
	ds_read_b64_tr_b16 v[142:143], v222 offset:31360
	s_waitcnt lgkmcnt(0)
	v_mfma_f32_16x16x32_bf16 v[64:67], v[140:143], v[132:135], v[64:67]
	v_mfma_f32_16x16x32_bf16 v[68:71], v[140:143], v[136:139], v[68:71]
	ds_read_b64_tr_b16 v[140:141], v222 offset:26784
	ds_read_b64_tr_b16 v[142:143], v222 offset:31392
	s_waitcnt lgkmcnt(0)
	v_mfma_f32_16x16x32_bf16 v[56:59], v[140:143], v[132:135], v[56:59]
	v_mfma_f32_16x16x32_bf16 v[60:63], v[140:143], v[136:139], v[60:63]
	ds_read_b64_tr_b16 v[140:141], v222 offset:26816
	ds_read_b64_tr_b16 v[142:143], v222 offset:31424
	s_waitcnt lgkmcnt(0)
	v_mfma_f32_16x16x32_bf16 v[48:51], v[140:143], v[132:135], v[48:51]
	v_mfma_f32_16x16x32_bf16 v[52:55], v[140:143], v[136:139], v[52:55]
	ds_read_b64_tr_b16 v[140:141], v213 offset:26624
	ds_read_b64_tr_b16 v[142:143], v213 offset:31232
	s_waitcnt lgkmcnt(0)
	v_mfma_f32_16x16x32_bf16 v[40:43], v[140:143], v[132:135], v[40:43]
	s_waitcnt vmcnt(3)
	v_lshlrev_b32_e32 v132, 16, v131
	v_and_b32_e32 v133, 0xffff0000, v131
	v_pk_mul_f32 v[134:135], v[132:133], v[132:133]
	v_mfma_f32_16x16x32_bf16 v[44:47], v[140:143], v[136:139], v[44:47]
	v_lshlrev_b32_e32 v142, 16, v128
	v_and_b32_e32 v143, 0xffff0000, v128
	v_lshlrev_b32_e32 v138, 16, v129
	v_and_b32_e32 v139, 0xffff0000, v129
	v_pk_mul_f32 v[128:129], v[142:143], v[142:143]
	v_pk_mul_f32 v[140:141], v[138:139], v[138:139]
	v_add_f32_e32 v128, v128, v129
	v_lshlrev_b32_e32 v136, 16, v130
	v_and_b32_e32 v137, 0xffff0000, v130
	v_add_f32_e32 v128, v140, v128
	v_pk_mul_f32 v[130:131], v[136:137], v[136:137]
	v_add_f32_e32 v128, v141, v128
	v_add_f32_e32 v128, v130, v128
	v_add_f32_e32 v128, v131, v128
	v_add_f32_e32 v128, v134, v128
	v_add_f32_e32 v128, v135, v128
	s_nop 1
	v_mov_b32_dpp v129, v128 quad_perm:[1,0,3,2] row_mask:0xf bank_mask:0xf
	s_waitcnt lgkmcnt(0)
	v_add_f32_e32 v128, v128, v129
	s_nop 1
	v_mov_b32_dpp v129, v128 quad_perm:[2,3,0,1] row_mask:0xf bank_mask:0xf
	s_waitcnt lgkmcnt(0)
	v_add_f32_e32 v128, v128, v129
	s_nop 1
	v_mov_b32_dpp v129, v128 row_half_mirror row_mask:0xf bank_mask:0xf
	s_waitcnt lgkmcnt(0)
; #define BAR_LDS() do { asm volatile("s_waitcnt lgkmcnt(0)" ::: "memory"); __builtin_amdgcn_s_barrier(); asm volatile("" ::: "memory"); } while (0)
; #define MEM_LOAD(kt) do { _Pragma("unroll") for (int ii = 0; ii < 2; ++ii) { const int cid = tid + 512 * ii; \
;         ukr[ii] = *(const u32x4*)(kvm + (size_t)((kt) * 64 + (cid >> 4)) * 1024 + hm * 128 + (cid & 15) * 8); \
;         uvr[ii] = *(const u32x4*)(kvm + (size_t)((kt) * 64 + (cid >> 4)) * 1024 + 512 + hm * 128 + (cid & 15) * 8); } } while (0)
; __device__ __forceinline__ void mem_unit(const Args& a, int l, LAS unsigned char* lds, int b, int hm, int qb) {
;     ...
;     MEM_STORE(0);
;     BAR_LDS();
;     for (int kt = 0; kt < 4; ++kt) {
;         if (kt < 3) MEM_LOAD(kt + 1);
;         attn_tile<128, false, 0>(Ks + (kt & 1) * 35840, 272, Vs + (kt & 1) * 35840, 288, qf, o, ol, fr, fq, 0, 0, 0, -gm, -gm);
;         if (kt < 3) MEM_STORE((kt + 1) & 1);
;         BAR_LDS();
;     }
;     ...
;             const u32x2 z = *(const u32x2*)(proj + row * NCOL + CZ + 1024 + hm * 128 + d0);
	v_add_f32_e32 v128, v128, v129
	s_nop 1
	v_mov_b32_dpp v129, v128 row_mirror row_mask:0xf bank_mask:0xf
	s_waitcnt lgkmcnt(0)
	v_add_f32_e32 v128, v128, v129
	v_fmamk_f32 v128, v128, 0x3c000000, v186
	v_rsq_f32_e32 v134, v128
	s_nop 0
	v_pk_mul_f32 v[128:129], v[134:135], v[142:143] op_sel_hi:[0,1]
	v_pk_mul_f32 v[130:131], v[134:135], v[138:139] op_sel_hi:[0,1]
	v_pk_mul_f32 v[128:129], v[4:5], v[128:129]
	v_pk_mul_f32 v[130:131], v[6:7], v[130:131]
	v_cvt_pk_bf16_f32 v128, v128, v129
	v_cvt_pk_bf16_f32 v129, v130, v131
	v_pk_mul_f32 v[130:131], v[134:135], v[136:137] op_sel_hi:[0,1]
	v_pk_mul_f32 v[132:133], v[134:135], v[132:133] op_sel_hi:[0,1]
	v_pk_mul_f32 v[130:131], v[0:1], v[130:131]
	v_pk_mul_f32 v[132:133], v[2:3], v[132:133]
	v_cvt_pk_bf16_f32 v130, v130, v131
	v_cvt_pk_bf16_f32 v131, v132, v133
	v_add_u32_e32 v132, v181, v174
	s_waitcnt vmcnt(1)
	v_lshlrev_b32_e32 v134, 16, v120
	v_and_b32_e32 v135, 0xffff0000, v120
	ds_write_b128 v132, v[128:131]
	v_lshlrev_b32_e32 v130, 16, v121
	v_and_b32_e32 v131, 0xffff0000, v121
	v_pk_mul_f32 v[120:121], v[134:135], v[134:135]
	v_add_u32_e32 v128, v181, v175
	v_pk_mul_f32 v[132:133], v[130:131], v[130:131]
	v_add_f32_e32 v120, v120, v121
	ds_write_b128 v128, v[124:127] offset:17408
	v_lshlrev_b32_e32 v128, 16, v122
	v_and_b32_e32 v129, 0xffff0000, v122
	v_add_f32_e32 v120, v132, v120
	v_lshlrev_b32_e32 v124, 16, v123
	v_and_b32_e32 v125, 0xffff0000, v123
	v_pk_mul_f32 v[122:123], v[128:129], v[128:129]
	v_add_f32_e32 v120, v133, v120
	v_add_f32_e32 v120, v122, v120
	v_pk_mul_f32 v[126:127], v[124:125], v[124:125]
	v_add_f32_e32 v120, v123, v120
	v_add_f32_e32 v120, v126, v120
	v_add_f32_e32 v120, v127, v120
	s_nop 1
	v_mov_b32_dpp v121, v120 quad_perm:[1,0,3,2] row_mask:0xf bank_mask:0xf
	s_waitcnt lgkmcnt(0)
	v_add_f32_e32 v120, v120, v121
	s_nop 1
	v_mov_b32_dpp v121, v120 quad_perm:[2,3,0,1] row_mask:0xf bank_mask:0xf
	s_waitcnt lgkmcnt(0)
	v_add_f32_e32 v120, v120, v121
	s_nop 1
	v_mov_b32_dpp v121, v120 row_half_mirror row_mask:0xf bank_mask:0xf
	s_waitcnt lgkmcnt(0)
	v_add_f32_e32 v120, v120, v121
	s_nop 1
	v_mov_b32_dpp v121, v120 row_mirror row_mask:0xf bank_mask:0xf
	s_waitcnt lgkmcnt(0)
	v_add_f32_e32 v120, v120, v121
	v_fmamk_f32 v120, v120, 0x3c000000, v186
	v_rsq_f32_e32 v126, v120
	s_nop 0
	v_pk_mul_f32 v[120:121], v[126:127], v[134:135] op_sel_hi:[0,1]
	v_pk_mul_f32 v[122:123], v[126:127], v[130:131] op_sel_hi:[0,1]
	v_pk_mul_f32 v[120:121], v[4:5], v[120:121]
	v_pk_mul_f32 v[122:123], v[6:7], v[122:123]
	v_cvt_pk_bf16_f32 v120, v120, v121
	v_cvt_pk_bf16_f32 v121, v122, v123
	v_pk_mul_f32 v[122:123], v[126:127], v[128:129] op_sel_hi:[0,1]
	v_pk_mul_f32 v[124:125], v[126:127], v[124:125] op_sel_hi:[0,1]
	v_pk_mul_f32 v[122:123], v[0:1], v[122:123]
	v_pk_mul_f32 v[124:125], v[2:3], v[124:125]
	v_cvt_pk_bf16_f32 v122, v122, v123
	v_cvt_pk_bf16_f32 v123, v124, v125
	v_add_u32_e32 v124, v181, v177
	ds_write_b128 v124, v[120:123]
	v_add_u32_e32 v120, v181, v180
	s_waitcnt vmcnt(0)
	ds_write_b128 v120, v[116:119] offset:17408
	s_waitcnt lgkmcnt(0)
	s_barrier
	s_cbranch_scc1 .LBB0_520
	ds_read_b128 v[0:3], v176 offset:35840
	ds_read_b128 v[118:121], v176 offset:35904
	v_add_u32_e32 v141, v172, v170
	v_add_u32_e32 v116, 0x4400, v172
	s_lshl_b32 s6, s8, 1
	v_lshlrev_b32_e32 v144, 1, v144
	s_mov_b64 s[4:5], 0x1400
	v_lshl_add_u64 v[164:165], v[162:163], 0, s[6:7]
	v_lshl_add_u64 v[166:167], v[158:159], 0, s[6:7]
	v_lshl_add_u64 v[164:165], v[164:165], 0, v[144:145]
	v_lshl_add_u64 v[166:167], v[166:167], 0, v[144:145]
	v_lshl_add_u64 v[164:165], v[164:165], 0, s[4:5]
	v_lshl_add_u64 v[166:167], v[166:167], 0, s[4:5]
	global_load_dwordx2 v[200:201], v[164:165], off
	global_load_dwordx2 v[202:203], v[164:165], off offset:32
	global_load_dwordx2 v[204:205], v[164:165], off offset:64
	global_load_dwordx2 v[206:207], v[164:165], off offset:96
	global_load_dwordx2 v[208:209], v[164:165], off offset:128
	global_load_dwordx2 v[210:211], v[164:165], off offset:160
	global_load_dwordx2 v[212:213], v[164:165], off offset:192
	global_load_dwordx2 v[214:215], v[164:165], off offset:224
	global_load_dwordx2 v[216:217], v[166:167], off
	global_load_dwordx2 v[218:219], v[166:167], off offset:32
	global_load_dwordx2 v[220:221], v[166:167], off offset:64
	global_load_dwordx2 v[222:223], v[166:167], off offset:96
	global_load_dwordx2 v[224:225], v[166:167], off offset:128
	global_load_dwordx2 v[226:227], v[166:167], off offset:160
	global_load_dwordx2 v[228:229], v[166:167], off offset:192
	global_load_dwordx2 v[230:231], v[166:167], off offset:224
	v_lshlrev_b32_e32 v142, 1, v144
	v_mov_b32_e32 v143, 0
	s_add_i32 s14, s14, s3
	s_cmpk_gt_i32 s14, 0xff
	s_waitcnt lgkmcnt(1)
	v_mfma_f32_16x16x32_bf16 v[4:7], v[0:3], v[16:19], v[72:75]
	ds_read_b128 v[126:129], v176 offset:40256
	ds_read_b128 v[134:137], v176 offset:44608
	v_mfma_f32_16x16x32_bf16 v[0:3], v[0:3], v[24:27], v[72:75]
	s_waitcnt lgkmcnt(2)
	v_mfma_f32_16x16x32_bf16 v[4:7], v[118:121], v[20:23], v[4:7]
	v_mfma_f32_16x16x32_bf16 v[0:3], v[118:121], v[28:31], v[0:3]
	ds_read_b128 v[118:121], v176 offset:35968
	s_waitcnt lgkmcnt(0)
	v_mfma_f32_16x16x32_bf16 v[4:7], v[118:121], v[12:15], v[4:7]
	v_mfma_f32_16x16x32_bf16 v[0:3], v[118:121], v[36:39], v[0:3]
	ds_read_b128 v[118:121], v176 offset:36032
	s_waitcnt lgkmcnt(0)
	v_mfma_f32_16x16x32_bf16 v[4:7], v[118:121], v[8:11], v[4:7]
	s_nop 7
	v_exp_f32_e32 v4, v4
	v_mfma_f32_16x16x32_bf16 v[0:3], v[118:121], v[32:35], v[0:3]
	ds_read_b128 v[118:121], v176 offset:40192
	v_exp_f32_e32 v5, v5
	v_exp_f32_e32 v6, v6
	s_waitcnt lgkmcnt(0)
; #define LAS __attribute__((address_space(3)))
; __device__ __forceinline__ unsigned pk2(float lo, float hi) { f32x2_t v = {lo, hi}; bf16x2_t b = __builtin_convertvector(v, bf16x2_t); return __builtin_bit_cast(unsigned, b); }
; __device__ __forceinline__ float ex2(float x) { return __builtin_amdgcn_exp2f(x); }
; #define MFMA16(a, b, c) __builtin_amdgcn_mfma_f32_16x16x32_bf16((a), (b), (c), 0, 0, 0)
; template <int D, bool DIAG, int QT0>
; __device__ __forceinline__ void sm_pv_tile(f32x4 (&s)[4][2], const LAS unsigned char* Vs, int VP, f32x4 (&o)[D / 16][2], f32x4 (&ol)[2], int fr, int fq, int keyl0, int qla, int qlb) {
; #pragma unroll
;     for (int qt = QT0; qt < 2; ++qt) {
;         if (DIAG) {
;             const int ql = (qt == 0 ? qla : qlb) + fr - keyl0 - fq * 4;
; #pragma unroll
;             for (int a = 0; a < 4; ++a)
; #pragma unroll
;                 for (int jj = 0; jj < 4; ++jj) s[a][qt][jj] = (a * 16 + jj > ql) ? -1e30f : s[a][qt][jj];
;         }
; #pragma unroll
;         for (int a = 0; a < 4; ++a)
; #pragma unroll
;             for (int jj = 0; jj < 4; ++jj) s[a][qt][jj] = ex2(s[a][qt][jj]);
;     }
; #pragma unroll
;     for (int kst = 0; kst < 2; ++kst) {
;         bf16x8 pb[2];
; #pragma unroll
;         for (int qt = QT0; qt < 2; ++qt) { u32x4 pw; pw.x = pk2(s[2 * kst][qt][0], s[2 * kst][qt][1]); pw.y = pk2(s[2 * kst][qt][2], s[2 * kst][qt][3]);
;             pw.z = pk2(s[2 * kst + 1][qt][0], s[2 * kst + 1][qt][1]); pw.w = pk2(s[2 * kst + 1][qt][2], s[2 * kst + 1][qt][3]); pb[qt] = __builtin_bit_cast(bf16x8, pw); }
;         if (QT0 == 0) ol[0] = MFMA16(ONES8, pb[0], ol[0]);
;         ol[1] = MFMA16(ONES8, pb[1], ol[1]);
; #pragma unroll
;         for (int dt = 0; dt < D / 16; ++dt) { const s16x4 lo = tr4(Vs, VP, kst * 32 + fq * 4, dt * 16, fr), hi = tr4(Vs, VP, kst * 32 + 16 + fq * 4, dt * 16, fr);
;             const bf16x8 vf = __builtin_shufflevector(lo, hi, 0, 1, 2, 3, 4, 5, 6, 7);
;             if (QT0 == 0) o[dt][0] = MFMA16(vf, pb[0], o[dt][0]);
;             o[dt][1] = MFMA16(vf, pb[1], o[dt][1]); }
;     }
	v_mfma_f32_16x16x32_bf16 v[122:125], v[118:121], v[16:19], v[72:75]
	v_exp_f32_e32 v7, v7
	s_nop 1
	v_exp_f32_e32 v0, v0
	v_exp_f32_e32 v1, v1
	v_mfma_f32_16x16x32_bf16 v[118:121], v[118:121], v[24:27], v[72:75]
	v_exp_f32_e32 v2, v2
	v_exp_f32_e32 v3, v3
	v_mfma_f32_16x16x32_bf16 v[122:125], v[126:129], v[20:23], v[122:125]
	v_mfma_f32_16x16x32_bf16 v[118:121], v[126:129], v[28:31], v[118:121]
	ds_read_b128 v[126:129], v176 offset:40320
	s_waitcnt lgkmcnt(0)
	v_mfma_f32_16x16x32_bf16 v[122:125], v[126:129], v[12:15], v[122:125]
	v_mfma_f32_16x16x32_bf16 v[118:121], v[126:129], v[36:39], v[118:121]
	ds_read_b128 v[126:129], v176 offset:40384
	s_waitcnt lgkmcnt(0)
	v_mfma_f32_16x16x32_bf16 v[122:125], v[126:129], v[8:11], v[122:125]
	v_mfma_f32_16x16x32_bf16 v[118:121], v[126:129], v[32:35], v[118:121]
	ds_read_b128 v[126:129], v176 offset:44544
	s_waitcnt lgkmcnt(0)
	v_mfma_f32_16x16x32_bf16 v[130:133], v[126:129], v[16:19], v[72:75]
	v_mfma_f32_16x16x32_bf16 v[126:129], v[126:129], v[24:27], v[72:75]
	v_mfma_f32_16x16x32_bf16 v[130:133], v[134:137], v[20:23], v[130:133]
	v_mfma_f32_16x16x32_bf16 v[126:129], v[134:137], v[28:31], v[126:129]
	ds_read_b128 v[134:137], v176 offset:44672
	s_waitcnt lgkmcnt(0)
	v_mfma_f32_16x16x32_bf16 v[130:133], v[134:137], v[12:15], v[130:133]
	v_mfma_f32_16x16x32_bf16 v[126:129], v[134:137], v[36:39], v[126:129]
	ds_read_b128 v[134:137], v176 offset:44736
	s_waitcnt lgkmcnt(0)
	v_mfma_f32_16x16x32_bf16 v[130:133], v[134:137], v[8:11], v[130:133]
	v_mfma_f32_16x16x32_bf16 v[126:129], v[134:137], v[32:35], v[126:129]
	ds_read_b128 v[134:137], v176 offset:48896
	s_waitcnt lgkmcnt(0)
	v_mfma_f32_16x16x32_bf16 v[16:19], v[134:137], v[16:19], v[72:75]
	s_nop 4
	v_exp_f32_e32 v117, v126
	v_mfma_f32_16x16x32_bf16 v[24:27], v[134:137], v[24:27], v[72:75]
	v_exp_f32_e32 v134, v127
	v_exp_f32_e32 v135, v128
	v_exp_f32_e32 v136, v129
	ds_read_b128 v[72:75], v176 offset:48960
	s_waitcnt lgkmcnt(0)
	v_mfma_f32_16x16x32_bf16 v[16:19], v[72:75], v[20:23], v[16:19]
	v_mfma_f32_16x16x32_bf16 v[20:23], v[72:75], v[28:31], v[24:27]
	s_nop 2
	ds_read_b128 v[24:27], v176 offset:49024
	s_waitcnt lgkmcnt(0)
	v_mfma_f32_16x16x32_bf16 v[12:15], v[24:27], v[12:15], v[16:19]
	v_mfma_f32_16x16x32_bf16 v[16:19], v[24:27], v[36:39], v[20:23]
	v_exp_f32_e32 v38, v132
	v_exp_f32_e32 v39, v133
	s_nop 0
	ds_read_b128 v[20:23], v176 offset:49088
	s_waitcnt lgkmcnt(0)
	v_mfma_f32_16x16x32_bf16 v[8:11], v[20:23], v[8:11], v[12:15]
	ds_read_b64_tr_b16 v[26:27], v141 offset:57856
	ds_read_b64_tr_b16 v[24:25], v141 offset:53248
	ds_read_b64_tr_b16 v[28:29], v141 offset:53280
	ds_read_b64_tr_b16 v[30:31], v141 offset:57888
	s_nop 3
	v_exp_f32_e32 v72, v8
	v_mfma_f32_16x16x32_bf16 v[12:15], v[20:23], v[32:35], v[16:19]
	v_exp_f32_e32 v73, v9
	v_exp_f32_e32 v74, v10
	v_exp_f32_e32 v75, v11
	v_exp_f32_e32 v16, v122
	v_exp_f32_e32 v17, v123
	v_exp_f32_e32 v18, v124
	v_exp_f32_e32 v19, v125
	v_exp_f32_e32 v8, v118
	v_exp_f32_e32 v9, v119
	v_exp_f32_e32 v10, v120
	v_exp_f32_e32 v11, v121
	v_exp_f32_e32 v137, v12
	v_exp_f32_e32 v138, v13
	v_exp_f32_e32 v139, v14
	v_exp_f32_e32 v140, v15
	v_cvt_pk_bf16_f32 v12, v4, v5
	v_cvt_pk_bf16_f32 v13, v6, v7
	v_cvt_pk_bf16_f32 v14, v16, v17
	v_cvt_pk_bf16_f32 v15, v18, v19
	v_cvt_pk_bf16_f32 v16, v0, v1
	v_cvt_pk_bf16_f32 v17, v2, v3
	v_cvt_pk_bf16_f32 v18, v8, v9
	v_cvt_pk_bf16_f32 v19, v10, v11
	s_waitcnt lgkmcnt(2)
	v_mfma_f32_16x16x32_bf16 v[20:23], v[24:27], v[12:15], v[84:87]
	v_mov_b64_e32 v[0:1], s[68:69]
	v_mov_b64_e32 v[2:3], s[70:71]
	v_exp_f32_e32 v32, v130
	v_mfma_f32_16x16x32_bf16 v[24:27], v[24:27], v[16:19], v[88:91]
	v_exp_f32_e32 v33, v131
	v_cvt_pk_bf16_f32 v72, v72, v73
	v_cvt_pk_bf16_f32 v73, v74, v75
	s_waitcnt lgkmcnt(0)
	v_mfma_f32_16x16x32_bf16 v[84:87], v[28:31], v[12:15], v[92:95]
	v_cvt_pk_bf16_f32 v74, v117, v134
	v_cvt_pk_bf16_f32 v75, v135, v136
	v_mfma_f32_16x16x32_bf16 v[88:91], v[28:31], v[16:19], v[96:99]
	ds_read_b64_tr_b16 v[28:29], v141 offset:53312
	ds_read_b64_tr_b16 v[30:31], v141 offset:57920
	s_waitcnt lgkmcnt(0)
	v_mfma_f32_16x16x32_bf16 v[96:99], v[28:31], v[16:19], v[80:83]
	s_nop 2
	v_add_u32_e32 v82, v172, v169
	v_add_u32_e32 v83, v172, v168
	v_mfma_f32_16x16x32_bf16 v[92:95], v[28:31], v[12:15], v[76:79]
	ds_read_b64_tr_b16 v[28:29], v82 offset:53248
	ds_read_b64_tr_b16 v[30:31], v82 offset:57856
	s_nop 0
	v_cvt_pk_bf16_f32 v76, v137, v138
	s_waitcnt lgkmcnt(0)
	v_mfma_f32_16x16x32_bf16 v[100:103], v[28:31], v[12:15], v[100:103]
	v_cvt_pk_bf16_f32 v77, v139, v140
	v_mfma_f32_16x16x32_bf16 v[104:107], v[28:31], v[16:19], v[104:107]
	ds_read_b64_tr_b16 v[28:29], v141 offset:53376
	ds_read_b64_tr_b16 v[30:31], v141 offset:57984
	v_mfma_f32_16x16x32_bf16 v[4:7], v[0:3], v[12:15], v[108:111]
	v_mfma_f32_16x16x32_bf16 v[8:11], v[0:3], v[16:19], v[112:115]
	s_waitcnt lgkmcnt(0)
	v_mfma_f32_16x16x32_bf16 v[108:111], v[28:31], v[12:15], v[64:67]
	v_mfma_f32_16x16x32_bf16 v[112:115], v[28:31], v[16:19], v[68:71]
	ds_read_b64_tr_b16 v[28:29], v141 offset:53408
	ds_read_b64_tr_b16 v[30:31], v141 offset:58016
	s_nop 0
	v_cvt_pk_bf16_f32 v70, v32, v33
	s_waitcnt lgkmcnt(0)
	v_mfma_f32_16x16x32_bf16 v[118:121], v[28:31], v[12:15], v[56:59]
	v_cvt_pk_bf16_f32 v71, v38, v39
	v_mfma_f32_16x16x32_bf16 v[122:125], v[28:31], v[16:19], v[60:63]
	ds_read_b64_tr_b16 v[28:29], v141 offset:53440
	ds_read_b64_tr_b16 v[30:31], v141 offset:58048
	s_waitcnt lgkmcnt(0)
	v_mfma_f32_16x16x32_bf16 v[126:129], v[28:31], v[12:15], v[48:51]
	v_mfma_f32_16x16x32_bf16 v[130:133], v[28:31], v[16:19], v[52:55]
	ds_read_b64_tr_b16 v[28:29], v83 offset:53248
	ds_read_b64_tr_b16 v[30:31], v83 offset:57856
	s_waitcnt lgkmcnt(0)
; __device__ __forceinline__ unsigned pk2(float lo, float hi) { f32x2_t v = {lo, hi}; bf16x2_t b = __builtin_convertvector(v, bf16x2_t); return __builtin_bit_cast(unsigned, b); }
; __device__ __forceinline__ float bflo(unsigned u) { return __uint_as_float(u << 16); }
; __device__ __forceinline__ float bfhi(unsigned u) { return __uint_as_float(u & 0xffff0000u); }
; __device__ __forceinline__ float frcp(float x) { return __builtin_amdgcn_rcpf(x); }
; template <int D, bool DIAG, int QT0>
; __device__ __forceinline__ void sm_pv_tile(f32x4 (&s)[4][2], const LAS unsigned char* Vs, int VP, f32x4 (&o)[D / 16][2], f32x4 (&ol)[2], int fr, int fq, int keyl0, int qla, int qlb) {
;     ...
;     for (int kst = 0; kst < 2; ++kst) {
;         bf16x8 pb[2];
; #pragma unroll
;         for (int qt = QT0; qt < 2; ++qt) { u32x4 pw; pw.x = pk2(s[2 * kst][qt][0], s[2 * kst][qt][1]); pw.y = pk2(s[2 * kst][qt][2], s[2 * kst][qt][3]);
;             pw.z = pk2(s[2 * kst + 1][qt][0], s[2 * kst + 1][qt][1]); pw.w = pk2(s[2 * kst + 1][qt][2], s[2 * kst + 1][qt][3]); pb[qt] = __builtin_bit_cast(bf16x8, pw); }
;         if (QT0 == 0) ol[0] = MFMA16(ONES8, pb[0], ol[0]);
;         ol[1] = MFMA16(ONES8, pb[1], ol[1]);
; #pragma unroll
;         for (int dt = 0; dt < D / 16; ++dt) { const s16x4 lo = tr4(Vs, VP, kst * 32 + fq * 4, dt * 16, fr), hi = tr4(Vs, VP, kst * 32 + 16 + fq * 4, dt * 16, fr);
;             const bf16x8 vf = __builtin_shufflevector(lo, hi, 0, 1, 2, 3, 4, 5, 6, 7);
;             if (QT0 == 0) o[dt][0] = MFMA16(vf, pb[0], o[dt][0]);
;             o[dt][1] = MFMA16(vf, pb[1], o[dt][1]); }
;     }
; __device__ __forceinline__ void mem_unit(const Args& a, int l, LAS unsigned char* lds, int b, int hm, int qb) {
;     ...
; #pragma unroll
;     for (int qt = 0; qt < 2; ++qt) {
;         const float inv = frcp(ol[qt][0]);
;         const size_t row = rowbase + q0 + qt * 16 + fr;
; #pragma unroll
;         for (int dt = 0; dt < 8; ++dt) { const int d0 = dt * 16 + fq * 4;
;             const u32x2 z = *(const u32x2*)(proj + row * NCOL + CZ + 1024 + hm * 128 + d0);
;             u32x2 y; y.x = pk2(o[dt][qt][0] * inv * silu(bflo(z.x)), o[dt][qt][1] * inv * silu(bfhi(z.x))); y.y = pk2(o[dt][qt][2] * inv * silu(bflo(z.y)), o[dt][qt][3] * inv * silu(bfhi(z.y)));
;             *(u32x2*)(proj + row * NCOL + CQM + hm * 128 + d0) = y; }
;     }
	v_mfma_f32_16x16x32_bf16 v[34:37], v[28:31], v[12:15], v[40:43]
	v_mfma_f32_16x16x32_bf16 v[66:69], v[28:31], v[16:19], v[44:47]
	v_mfma_f32_16x16x32_bf16 v[62:65], v[0:3], v[70:73], v[4:7]
	v_mfma_f32_16x16x32_bf16 v[28:31], v[0:3], v[74:77], v[8:11]
	ds_read_b64_tr_b16 v[0:1], v141 offset:62464
	s_nop 0
	v_add_u32_e32 v6, v116, v170
	ds_read_b64_tr_b16 v[2:3], v6 offset:49664
	ds_read_b64_tr_b16 v[4:5], v6 offset:49696
	s_waitcnt lgkmcnt(1)
	v_mfma_f32_16x16x32_bf16 v[78:81], v[0:3], v[70:73], v[20:23]
	v_lshl_add_u64 v[64:65], v[162:163], 0, s[6:7]
	v_lshl_add_u64 v[64:65], v[64:65], 0, v[144:145]
	v_rcp_f32_e32 v62, v62
	v_mfma_f32_16x16x32_bf16 v[30:33], v[0:3], v[74:77], v[24:27]
	ds_read_b64_tr_b16 v[2:3], v141 offset:62496
	s_waitcnt lgkmcnt(0)
	v_mfma_f32_16x16x32_bf16 v[58:61], v[2:5], v[70:73], v[84:87]
	s_nop 7
	v_pk_mul_f32 v[58:59], v[62:63], v[58:59] op_sel_hi:[0,1]
	v_mfma_f32_16x16x32_bf16 v[24:27], v[2:5], v[74:77], v[88:91]
	ds_read_b64_tr_b16 v[0:1], v141 offset:62528
	ds_read_b64_tr_b16 v[2:3], v6 offset:49728
	v_pk_mul_f32 v[60:61], v[62:63], v[60:61] op_sel_hi:[0,1]
	s_waitcnt lgkmcnt(0)
	v_mfma_f32_16x16x32_bf16 v[54:57], v[0:3], v[70:73], v[92:95]
	v_mfma_f32_16x16x32_bf16 v[20:23], v[0:3], v[74:77], v[96:99]
	v_add_u32_e32 v2, v116, v169
	ds_read_b64_tr_b16 v[0:1], v82 offset:62464
	ds_read_b64_tr_b16 v[2:3], v2 offset:49664
	s_waitcnt lgkmcnt(0)
	v_mfma_f32_16x16x32_bf16 v[50:53], v[0:3], v[70:73], v[100:103]
	s_nop 1
	v_mul_f32_e64 v54, v62, v54
	v_mul_f32_e64 v55, v62, v55
	v_pk_mul_f32 v[56:57], v[62:63], v[56:57] op_sel_hi:[0,1]
	s_nop 2
	v_pk_mul_f32 v[50:51], v[62:63], v[50:51] op_sel_hi:[0,1]
	v_mfma_f32_16x16x32_bf16 v[16:19], v[0:3], v[74:77], v[104:107]
	ds_read_b64_tr_b16 v[0:1], v141 offset:62592
	ds_read_b64_tr_b16 v[2:3], v6 offset:49792
	v_pk_mul_f32 v[52:53], v[62:63], v[52:53] op_sel_hi:[0,1]
	s_waitcnt lgkmcnt(0)
	v_mfma_f32_16x16x32_bf16 v[46:49], v[0:3], v[70:73], v[108:111]
	v_mfma_f32_16x16x32_bf16 v[12:15], v[0:3], v[74:77], v[112:115]
	ds_read_b64_tr_b16 v[0:1], v141 offset:62624
	ds_read_b64_tr_b16 v[2:3], v6 offset:49824
	s_nop 4
	v_pk_mul_f32 v[46:47], v[62:63], v[46:47] op_sel_hi:[0,1]
	v_pk_mul_f32 v[48:49], v[62:63], v[48:49] op_sel_hi:[0,1]
	s_waitcnt lgkmcnt(0)
	v_mfma_f32_16x16x32_bf16 v[42:45], v[0:3], v[70:73], v[118:121]
	v_mfma_f32_16x16x32_bf16 v[8:11], v[0:3], v[74:77], v[122:125]
	ds_read_b64_tr_b16 v[0:1], v141 offset:62656
	ds_read_b64_tr_b16 v[2:3], v6 offset:49856
	s_nop 4
	v_pk_mul_f32 v[42:43], v[62:63], v[42:43] op_sel_hi:[0,1]
	v_pk_mul_f32 v[44:45], v[62:63], v[44:45] op_sel_hi:[0,1]
	s_waitcnt lgkmcnt(0)
	v_mfma_f32_16x16x32_bf16 v[38:41], v[0:3], v[70:73], v[126:129]
	v_mfma_f32_16x16x32_bf16 v[4:7], v[0:3], v[74:77], v[130:133]
	v_add_u32_e32 v2, v116, v168
	ds_read_b64_tr_b16 v[0:1], v83 offset:62464
	ds_read_b64_tr_b16 v[2:3], v2 offset:49664
	s_waitcnt lgkmcnt(0)
	v_mfma_f32_16x16x32_bf16 v[34:37], v[0:3], v[70:73], v[34:37]
	s_waitcnt lgkmcnt(0)
	s_barrier
	v_mfma_f32_16x16x32_bf16 v[0:3], v[0:3], v[74:77], v[66:69]
	v_mul_f32_e64 v72, v62, v78
	v_mul_f32_e64 v73, v62, v79
	v_pk_mul_f32 v[38:39], v[62:63], v[38:39] op_sel_hi:[0,1]
	v_pk_mul_f32 v[40:41], v[62:63], v[40:41] op_sel_hi:[0,1]
	v_lshl_add_u64 v[66:67], v[64:65], 0, s[4:5]
	v_add_co_u32_e32 v64, vcc, s26, v64
	v_pk_mul_f32 v[34:35], v[62:63], v[34:35] op_sel_hi:[0,1]
	s_nop 0
	v_addc_co_u32_e32 v65, vcc, 0, v65, vcc
	s_waitcnt vmcnt(0)
	v_mov_b64_e32 v[64:65], v[200:201]
	v_pk_mul_f32 v[36:37], v[62:63], v[36:37] op_sel_hi:[0,1]
	s_waitcnt vmcnt(0)
	v_lshlrev_b32_e32 v68, 16, v64
	v_mul_f32_e32 v29, 0xbfb8aa3b, v68
	v_exp_f32_e32 v29, v29
	v_and_b32_e32 v69, 0xffff0000, v64
	v_lshlrev_b32_e32 v64, 16, v65
	v_and_b32_e32 v65, 0xffff0000, v65
	v_add_f32_e32 v29, 1.0, v29
	v_rcp_f32_e32 v70, v29
	v_mul_f32_e32 v29, 0xbfb8aa3b, v69
	v_exp_f32_e32 v29, v29
	s_nop 0
	v_add_f32_e32 v29, 1.0, v29
	v_rcp_f32_e32 v71, v29
	v_mul_f32_e32 v29, 0xbfb8aa3b, v64
	v_exp_f32_e32 v29, v29
	v_pk_mul_f32 v[68:69], v[70:71], v[68:69]
	s_nop 0
	v_pk_mul_f32 v[68:69], v[72:73], v[68:69]
	v_add_f32_e32 v29, 1.0, v29
	v_rcp_f32_e32 v70, v29
	v_mul_f32_e32 v29, 0xbfb8aa3b, v65
	v_exp_f32_e32 v29, v29
	v_pk_mul_f32 v[72:73], v[62:63], v[80:81] op_sel_hi:[0,1]
	v_cvt_pk_bf16_f32 v68, v68, v69
	v_add_f32_e32 v29, 1.0, v29
	v_rcp_f32_e32 v71, v29
	s_nop 0
	v_pk_mul_f32 v[64:65], v[70:71], v[64:65]
	s_nop 0
	v_pk_mul_f32 v[64:65], v[72:73], v[64:65]
	s_nop 0
	v_cvt_pk_bf16_f32 v69, v64, v65
	v_lshl_add_u64 v[64:65], v[160:161], 0, v[142:143]
	v_mov_b64_e32 v[232:233], v[68:69]
	v_mov_b64_e32 v[68:69], v[202:203]
	v_lshlrev_b32_e32 v70, 16, v68
	v_mul_f32_e32 v29, 0xbfb8aa3b, v70
	v_exp_f32_e32 v29, v29
	v_and_b32_e32 v71, 0xffff0000, v68
	v_lshlrev_b32_e32 v68, 16, v69
	v_and_b32_e32 v69, 0xffff0000, v69
	v_add_f32_e32 v29, 1.0, v29
	v_rcp_f32_e32 v72, v29
	v_mul_f32_e32 v29, 0xbfb8aa3b, v71
	v_exp_f32_e32 v29, v29
	s_nop 0
	v_add_f32_e32 v29, 1.0, v29
	v_rcp_f32_e32 v73, v29
	v_mul_f32_e32 v29, 0xbfb8aa3b, v68
	v_exp_f32_e32 v29, v29
	v_pk_mul_f32 v[70:71], v[72:73], v[70:71]
	s_nop 0
	v_pk_mul_f32 v[58:59], v[58:59], v[70:71]
	v_add_f32_e32 v29, 1.0, v29
	v_rcp_f32_e32 v70, v29
	v_mul_f32_e32 v29, 0xbfb8aa3b, v69
	v_exp_f32_e32 v29, v29
	v_cvt_pk_bf16_f32 v58, v58, v59
	v_add_f32_e32 v29, 1.0, v29
	v_rcp_f32_e32 v71, v29
	s_nop 0
	v_pk_mul_f32 v[68:69], v[70:71], v[68:69]
	s_nop 0
	v_pk_mul_f32 v[60:61], v[60:61], v[68:69]
	s_nop 0
	v_cvt_pk_bf16_f32 v59, v60, v61
	v_mov_b64_e32 v[234:235], v[58:59]
	global_store_dwordx4 v[64:65], v[232:235], off offset:2048 sc1
	v_mov_b64_e32 v[58:59], v[204:205]
	v_lshlrev_b32_e32 v60, 16, v58
; __device__ __forceinline__ unsigned pk2(float lo, float hi) { f32x2_t v = {lo, hi}; bf16x2_t b = __builtin_convertvector(v, bf16x2_t); return __builtin_bit_cast(unsigned, b); }
; __device__ __forceinline__ float bflo(unsigned u) { return __uint_as_float(u << 16); }
; __device__ __forceinline__ float bfhi(unsigned u) { return __uint_as_float(u & 0xffff0000u); }
; __device__ __forceinline__ float frcp(float x) { return __builtin_amdgcn_rcpf(x); }
; __device__ __forceinline__ float silu(float x) { return x * frcp(1.f + fexp(-x)); }
; __device__ __forceinline__ void mem_unit(const Args& a, int l, LAS unsigned char* lds, int b, int hm, int qb) {
;     ...
; #pragma unroll
;     for (int qt = 0; qt < 2; ++qt) {
;         const float inv = frcp(ol[qt][0]);
;         const size_t row = rowbase + q0 + qt * 16 + fr;
; #pragma unroll
;         for (int dt = 0; dt < 8; ++dt) { const int d0 = dt * 16 + fq * 4;
;             const u32x2 z = *(const u32x2*)(proj + row * NCOL + CZ + 1024 + hm * 128 + d0);
;             u32x2 y; y.x = pk2(o[dt][qt][0] * inv * silu(bflo(z.x)), o[dt][qt][1] * inv * silu(bfhi(z.x))); y.y = pk2(o[dt][qt][2] * inv * silu(bflo(z.y)), o[dt][qt][3] * inv * silu(bfhi(z.y)));
;             *(u32x2*)(proj + row * NCOL + CQM + hm * 128 + d0) = y; }
;     }
	v_mul_f32_e32 v29, 0xbfb8aa3b, v60
	v_exp_f32_e32 v29, v29
	v_and_b32_e32 v61, 0xffff0000, v58
	v_lshlrev_b32_e32 v58, 16, v59
	v_and_b32_e32 v59, 0xffff0000, v59
	v_add_f32_e32 v29, 1.0, v29
	v_rcp_f32_e32 v68, v29
	v_mul_f32_e32 v29, 0xbfb8aa3b, v61
	v_exp_f32_e32 v29, v29
	s_nop 0
	v_add_f32_e32 v29, 1.0, v29
	v_rcp_f32_e32 v69, v29
	v_mul_f32_e32 v29, 0xbfb8aa3b, v58
	v_exp_f32_e32 v29, v29
	v_pk_mul_f32 v[60:61], v[68:69], v[60:61]
	s_nop 0
	v_pk_mul_f32 v[54:55], v[54:55], v[60:61]
	v_add_f32_e32 v29, 1.0, v29
	v_rcp_f32_e32 v60, v29
	v_mul_f32_e32 v29, 0xbfb8aa3b, v59
	v_exp_f32_e32 v29, v29
	v_cvt_pk_bf16_f32 v54, v54, v55
	v_add_f32_e32 v29, 1.0, v29
	v_rcp_f32_e32 v61, v29
	s_nop 0
	v_pk_mul_f32 v[58:59], v[60:61], v[58:59]
	s_nop 0
	v_pk_mul_f32 v[56:57], v[56:57], v[58:59]
	s_nop 0
	v_cvt_pk_bf16_f32 v55, v56, v57
	v_mov_b64_e32 v[236:237], v[54:55]
	v_mov_b64_e32 v[54:55], v[206:207]
	v_lshlrev_b32_e32 v56, 16, v54
	v_mul_f32_e32 v29, 0xbfb8aa3b, v56
	v_exp_f32_e32 v29, v29
	v_and_b32_e32 v57, 0xffff0000, v54
	v_lshlrev_b32_e32 v54, 16, v55
	v_and_b32_e32 v55, 0xffff0000, v55
	v_add_f32_e32 v29, 1.0, v29
	v_rcp_f32_e32 v58, v29
	v_mul_f32_e32 v29, 0xbfb8aa3b, v57
	v_exp_f32_e32 v29, v29
	s_nop 0
	v_add_f32_e32 v29, 1.0, v29
	v_rcp_f32_e32 v59, v29
	v_mul_f32_e32 v29, 0xbfb8aa3b, v54
	v_exp_f32_e32 v29, v29
	v_pk_mul_f32 v[56:57], v[58:59], v[56:57]
	s_nop 0
	v_pk_mul_f32 v[50:51], v[50:51], v[56:57]
	v_add_f32_e32 v29, 1.0, v29
	v_rcp_f32_e32 v56, v29
	v_mul_f32_e32 v29, 0xbfb8aa3b, v55
	v_exp_f32_e32 v29, v29
	v_cvt_pk_bf16_f32 v50, v50, v51
	v_add_f32_e32 v29, 1.0, v29
	v_rcp_f32_e32 v57, v29
	s_nop 0
	v_pk_mul_f32 v[54:55], v[56:57], v[54:55]
	s_nop 0
	v_pk_mul_f32 v[52:53], v[52:53], v[54:55]
	s_nop 0
	v_cvt_pk_bf16_f32 v51, v52, v53
	v_mov_b64_e32 v[238:239], v[50:51]
	global_store_dwordx4 v[64:65], v[236:239], off offset:2112 sc1
	v_mov_b64_e32 v[50:51], v[208:209]
	v_lshlrev_b32_e32 v52, 16, v50
	v_mul_f32_e32 v29, 0xbfb8aa3b, v52
	v_exp_f32_e32 v29, v29
	v_and_b32_e32 v53, 0xffff0000, v50
	v_lshlrev_b32_e32 v50, 16, v51
	v_and_b32_e32 v51, 0xffff0000, v51
	v_add_f32_e32 v29, 1.0, v29
	v_rcp_f32_e32 v54, v29
	v_mul_f32_e32 v29, 0xbfb8aa3b, v53
	v_exp_f32_e32 v29, v29
	s_nop 0
	v_add_f32_e32 v29, 1.0, v29
	v_rcp_f32_e32 v55, v29
	v_mul_f32_e32 v29, 0xbfb8aa3b, v50
	v_exp_f32_e32 v29, v29
	v_pk_mul_f32 v[52:53], v[54:55], v[52:53]
	s_nop 0
	v_pk_mul_f32 v[46:47], v[46:47], v[52:53]
	v_add_f32_e32 v29, 1.0, v29
	v_rcp_f32_e32 v52, v29
	v_mul_f32_e32 v29, 0xbfb8aa3b, v51
	v_exp_f32_e32 v29, v29
	v_cvt_pk_bf16_f32 v46, v46, v47
	v_add_f32_e32 v29, 1.0, v29
	v_rcp_f32_e32 v53, v29
	s_nop 0
	v_pk_mul_f32 v[50:51], v[52:53], v[50:51]
	s_nop 0
	v_pk_mul_f32 v[48:49], v[48:49], v[50:51]
	s_nop 0
	v_cvt_pk_bf16_f32 v47, v48, v49
	v_mov_b64_e32 v[240:241], v[46:47]
	v_mov_b64_e32 v[46:47], v[210:211]
	v_lshlrev_b32_e32 v48, 16, v46
	v_mul_f32_e32 v29, 0xbfb8aa3b, v48
	v_exp_f32_e32 v29, v29
	v_and_b32_e32 v49, 0xffff0000, v46
	v_lshlrev_b32_e32 v46, 16, v47
	v_and_b32_e32 v47, 0xffff0000, v47
	v_add_f32_e32 v29, 1.0, v29
	v_rcp_f32_e32 v50, v29
	v_mul_f32_e32 v29, 0xbfb8aa3b, v49
	v_exp_f32_e32 v29, v29
	s_nop 0
	v_add_f32_e32 v29, 1.0, v29
	v_rcp_f32_e32 v51, v29
	v_mul_f32_e32 v29, 0xbfb8aa3b, v46
	v_exp_f32_e32 v29, v29
	v_pk_mul_f32 v[48:49], v[50:51], v[48:49]
	s_nop 0
	v_pk_mul_f32 v[42:43], v[42:43], v[48:49]
	v_add_f32_e32 v29, 1.0, v29
	v_rcp_f32_e32 v48, v29
	v_mul_f32_e32 v29, 0xbfb8aa3b, v47
	v_exp_f32_e32 v29, v29
	v_cvt_pk_bf16_f32 v42, v42, v43
	v_add_f32_e32 v29, 1.0, v29
	v_rcp_f32_e32 v49, v29
	s_nop 0
	v_pk_mul_f32 v[46:47], v[48:49], v[46:47]
	s_nop 0
	v_pk_mul_f32 v[44:45], v[44:45], v[46:47]
	s_nop 0
	v_cvt_pk_bf16_f32 v43, v44, v45
	v_mov_b64_e32 v[242:243], v[42:43]
	global_store_dwordx4 v[64:65], v[240:243], off offset:2176 sc1
	v_mov_b64_e32 v[42:43], v[212:213]
	v_lshlrev_b32_e32 v44, 16, v42
	v_mul_f32_e32 v29, 0xbfb8aa3b, v44
	v_exp_f32_e32 v29, v29
	v_and_b32_e32 v45, 0xffff0000, v42
	v_lshlrev_b32_e32 v42, 16, v43
	v_and_b32_e32 v43, 0xffff0000, v43
	v_add_f32_e32 v29, 1.0, v29
	v_rcp_f32_e32 v46, v29
	v_mul_f32_e32 v29, 0xbfb8aa3b, v45
	v_exp_f32_e32 v29, v29
	s_nop 0
	v_add_f32_e32 v29, 1.0, v29
	v_rcp_f32_e32 v47, v29
	v_mul_f32_e32 v29, 0xbfb8aa3b, v42
	v_exp_f32_e32 v29, v29
	v_pk_mul_f32 v[44:45], v[46:47], v[44:45]
	s_nop 0
	v_pk_mul_f32 v[38:39], v[38:39], v[44:45]
	v_add_f32_e32 v29, 1.0, v29
	v_rcp_f32_e32 v44, v29
	v_mul_f32_e32 v29, 0xbfb8aa3b, v43
	v_exp_f32_e32 v29, v29
	v_cvt_pk_bf16_f32 v38, v38, v39
	v_add_f32_e32 v29, 1.0, v29
	v_rcp_f32_e32 v45, v29
	s_nop 0
	v_pk_mul_f32 v[42:43], v[44:45], v[42:43]
	s_nop 0
	v_pk_mul_f32 v[40:41], v[40:41], v[42:43]
	s_nop 0
	v_cvt_pk_bf16_f32 v39, v40, v41
	v_mov_b64_e32 v[180:181], v[38:39]
	v_mov_b64_e32 v[38:39], v[214:215]
	v_lshlrev_b32_e32 v40, 16, v38
	v_mul_f32_e32 v29, 0xbfb8aa3b, v40
	v_exp_f32_e32 v29, v29
	v_and_b32_e32 v41, 0xffff0000, v38
	v_lshlrev_b32_e32 v38, 16, v39
	v_and_b32_e32 v39, 0xffff0000, v39
	v_add_f32_e32 v29, 1.0, v29
	v_rcp_f32_e32 v42, v29
	v_mul_f32_e32 v29, 0xbfb8aa3b, v41
	v_exp_f32_e32 v29, v29
	s_nop 0
	v_add_f32_e32 v29, 1.0, v29
	v_rcp_f32_e32 v43, v29
	v_mul_f32_e32 v29, 0xbfb8aa3b, v38
	v_exp_f32_e32 v29, v29
	v_pk_mul_f32 v[40:41], v[42:43], v[40:41]
	s_nop 0
	v_pk_mul_f32 v[34:35], v[34:35], v[40:41]
	v_add_f32_e32 v29, 1.0, v29
	v_rcp_f32_e32 v40, v29
	v_mul_f32_e32 v29, 0xbfb8aa3b, v39
	v_exp_f32_e32 v29, v29
	v_cvt_pk_bf16_f32 v34, v34, v35
	v_add_f32_e32 v29, 1.0, v29
	v_rcp_f32_e32 v41, v29
	s_nop 0
	v_pk_mul_f32 v[38:39], v[40:41], v[38:39]
	s_nop 0
	v_pk_mul_f32 v[36:37], v[36:37], v[38:39]
; __device__ __forceinline__ unsigned pk2(float lo, float hi) { f32x2_t v = {lo, hi}; bf16x2_t b = __builtin_convertvector(v, bf16x2_t); return __builtin_bit_cast(unsigned, b); }
; __device__ __forceinline__ float bflo(unsigned u) { return __uint_as_float(u << 16); }
; __device__ __forceinline__ float bfhi(unsigned u) { return __uint_as_float(u & 0xffff0000u); }
; __device__ __forceinline__ float frcp(float x) { return __builtin_amdgcn_rcpf(x); }
; __device__ __forceinline__ float silu(float x) { return x * frcp(1.f + fexp(-x)); }
; __device__ __forceinline__ void mem_unit(const Args& a, int l, LAS unsigned char* lds, int b, int hm, int qb) {
;     ...
; #pragma unroll
;     for (int qt = 0; qt < 2; ++qt) {
;         const float inv = frcp(ol[qt][0]);
;         const size_t row = rowbase + q0 + qt * 16 + fr;
; #pragma unroll
;         for (int dt = 0; dt < 8; ++dt) { const int d0 = dt * 16 + fq * 4;
;             const u32x2 z = *(const u32x2*)(proj + row * NCOL + CZ + 1024 + hm * 128 + d0);
;             u32x2 y; y.x = pk2(o[dt][qt][0] * inv * silu(bflo(z.x)), o[dt][qt][1] * inv * silu(bfhi(z.x))); y.y = pk2(o[dt][qt][2] * inv * silu(bflo(z.y)), o[dt][qt][3] * inv * silu(bfhi(z.y)));
;             *(u32x2*)(proj + row * NCOL + CQM + hm * 128 + d0) = y; }
;     }
	s_nop 0
	v_cvt_pk_bf16_f32 v35, v36, v37
	v_mov_b64_e32 v[182:183], v[34:35]
	global_store_dwordx4 v[64:65], v[180:183], off offset:2240 sc1
	v_rcp_f32_e32 v34, v28
	v_lshl_add_u64 v[28:29], v[158:159], 0, s[6:7]
	v_lshl_add_u64 v[28:29], v[28:29], 0, v[144:145]
	v_lshl_add_u64 v[36:37], v[28:29], 0, s[4:5]
	v_add_co_u32_e32 v28, vcc, s26, v28
	v_pk_mul_f32 v[30:31], v[34:35], v[30:31] op_sel_hi:[0,1]
	s_nop 0
	v_addc_co_u32_e32 v29, vcc, 0, v29, vcc
	v_mov_b64_e32 v[28:29], v[216:217]
	v_pk_mul_f32 v[32:33], v[34:35], v[32:33] op_sel_hi:[0,1]
	v_pk_mul_f32 v[24:25], v[34:35], v[24:25] op_sel_hi:[0,1]
	v_pk_mul_f32 v[26:27], v[34:35], v[26:27] op_sel_hi:[0,1]
	v_pk_mul_f32 v[20:21], v[34:35], v[20:21] op_sel_hi:[0,1]
	v_pk_mul_f32 v[22:23], v[34:35], v[22:23] op_sel_hi:[0,1]
	v_pk_mul_f32 v[16:17], v[34:35], v[16:17] op_sel_hi:[0,1]
	v_pk_mul_f32 v[18:19], v[34:35], v[18:19] op_sel_hi:[0,1]
	v_pk_mul_f32 v[12:13], v[34:35], v[12:13] op_sel_hi:[0,1]
	v_pk_mul_f32 v[14:15], v[34:35], v[14:15] op_sel_hi:[0,1]
	v_pk_mul_f32 v[8:9], v[34:35], v[8:9] op_sel_hi:[0,1]
	v_pk_mul_f32 v[10:11], v[34:35], v[10:11] op_sel_hi:[0,1]
	v_pk_mul_f32 v[4:5], v[34:35], v[4:5] op_sel_hi:[0,1]
	v_pk_mul_f32 v[6:7], v[34:35], v[6:7] op_sel_hi:[0,1]
	v_pk_mul_f32 v[0:1], v[34:35], v[0:1] op_sel_hi:[0,1]
	v_pk_mul_f32 v[2:3], v[34:35], v[2:3] op_sel_hi:[0,1]
	v_lshlrev_b32_e32 v38, 16, v28
	v_and_b32_e32 v39, 0xffff0000, v28
	v_mul_f32_e32 v28, 0xbfb8aa3b, v38
	v_exp_f32_e32 v28, v28
	s_nop 0
	v_add_f32_e32 v28, 1.0, v28
	v_rcp_f32_e32 v40, v28
	v_mul_f32_e32 v28, 0xbfb8aa3b, v39
	v_exp_f32_e32 v28, v28
	s_nop 0
	v_add_f32_e32 v28, 1.0, v28
	v_rcp_f32_e32 v41, v28
	v_lshlrev_b32_e32 v28, 16, v29
	v_and_b32_e32 v29, 0xffff0000, v29
	v_pk_mul_f32 v[38:39], v[40:41], v[38:39]
	s_nop 0
	v_pk_mul_f32 v[30:31], v[30:31], v[38:39]
	s_nop 0
	v_cvt_pk_bf16_f32 v30, v30, v31
	v_mul_f32_e32 v31, 0xbfb8aa3b, v28
	v_exp_f32_e32 v31, v31
	s_nop 0
	v_add_f32_e32 v31, 1.0, v31
	v_rcp_f32_e32 v38, v31
	v_mul_f32_e32 v31, 0xbfb8aa3b, v29
	v_exp_f32_e32 v31, v31
	s_nop 0
	v_add_f32_e32 v31, 1.0, v31
	v_rcp_f32_e32 v39, v31
	s_nop 0
	v_pk_mul_f32 v[28:29], v[38:39], v[28:29]
	s_nop 0
	v_pk_mul_f32 v[28:29], v[32:33], v[28:29]
	s_nop 0
	v_cvt_pk_bf16_f32 v31, v28, v29
	v_lshl_add_u64 v[28:29], v[156:157], 0, v[142:143]
	v_mov_b64_e32 v[232:233], v[30:31]
	v_mov_b64_e32 v[30:31], v[218:219]
	v_lshlrev_b32_e32 v32, 16, v30
	v_and_b32_e32 v33, 0xffff0000, v30
	v_mul_f32_e32 v30, 0xbfb8aa3b, v32
	v_exp_f32_e32 v30, v30
	s_nop 0
	v_add_f32_e32 v30, 1.0, v30
	v_rcp_f32_e32 v38, v30
	v_mul_f32_e32 v30, 0xbfb8aa3b, v33
	v_exp_f32_e32 v30, v30
	s_nop 0
	v_add_f32_e32 v30, 1.0, v30
	v_rcp_f32_e32 v39, v30
	v_lshlrev_b32_e32 v30, 16, v31
	v_and_b32_e32 v31, 0xffff0000, v31
	v_pk_mul_f32 v[32:33], v[38:39], v[32:33]
	s_nop 0
	v_pk_mul_f32 v[24:25], v[24:25], v[32:33]
	s_nop 0
	v_cvt_pk_bf16_f32 v24, v24, v25
	v_mul_f32_e32 v25, 0xbfb8aa3b, v30
	v_exp_f32_e32 v25, v25
	s_nop 0
	v_add_f32_e32 v25, 1.0, v25
	v_rcp_f32_e32 v32, v25
	v_mul_f32_e32 v25, 0xbfb8aa3b, v31
	v_exp_f32_e32 v25, v25
	s_nop 0
	v_add_f32_e32 v25, 1.0, v25
	v_rcp_f32_e32 v33, v25
	s_nop 0
	v_pk_mul_f32 v[30:31], v[32:33], v[30:31]
	s_nop 0
	v_pk_mul_f32 v[26:27], v[26:27], v[30:31]
	s_nop 0
	v_cvt_pk_bf16_f32 v25, v26, v27
	v_mov_b64_e32 v[234:235], v[24:25]
	global_store_dwordx4 v[28:29], v[232:235], off offset:2048 sc1
	v_mov_b64_e32 v[24:25], v[220:221]
	v_lshlrev_b32_e32 v26, 16, v24
	v_and_b32_e32 v27, 0xffff0000, v24
	v_mul_f32_e32 v24, 0xbfb8aa3b, v26
	v_exp_f32_e32 v24, v24
	s_nop 0
	v_add_f32_e32 v24, 1.0, v24
	v_rcp_f32_e32 v30, v24
	v_mul_f32_e32 v24, 0xbfb8aa3b, v27
	v_exp_f32_e32 v24, v24
	s_nop 0
	v_add_f32_e32 v24, 1.0, v24
	v_rcp_f32_e32 v31, v24
	v_lshlrev_b32_e32 v24, 16, v25
	v_and_b32_e32 v25, 0xffff0000, v25
	v_pk_mul_f32 v[26:27], v[30:31], v[26:27]
	s_nop 0
	v_pk_mul_f32 v[20:21], v[20:21], v[26:27]
	s_nop 0
	v_cvt_pk_bf16_f32 v20, v20, v21
	v_mul_f32_e32 v21, 0xbfb8aa3b, v24
	v_exp_f32_e32 v21, v21
	s_nop 0
	v_add_f32_e32 v21, 1.0, v21
	v_rcp_f32_e32 v26, v21
	v_mul_f32_e32 v21, 0xbfb8aa3b, v25
	v_exp_f32_e32 v21, v21
	s_nop 0
	v_add_f32_e32 v21, 1.0, v21
	v_rcp_f32_e32 v27, v21
	s_nop 0
	v_pk_mul_f32 v[24:25], v[26:27], v[24:25]
	s_nop 0
	v_pk_mul_f32 v[22:23], v[22:23], v[24:25]
	s_nop 0
	v_cvt_pk_bf16_f32 v21, v22, v23
	v_mov_b64_e32 v[236:237], v[20:21]
	v_mov_b64_e32 v[20:21], v[222:223]
	v_lshlrev_b32_e32 v22, 16, v20
	v_and_b32_e32 v23, 0xffff0000, v20
	v_mul_f32_e32 v20, 0xbfb8aa3b, v22
	v_exp_f32_e32 v20, v20
	s_nop 0
	v_add_f32_e32 v20, 1.0, v20
	v_rcp_f32_e32 v24, v20
	v_mul_f32_e32 v20, 0xbfb8aa3b, v23
	v_exp_f32_e32 v20, v20
	s_nop 0
; __device__ __forceinline__ unsigned pk2(float lo, float hi) { f32x2_t v = {lo, hi}; bf16x2_t b = __builtin_convertvector(v, bf16x2_t); return __builtin_bit_cast(unsigned, b); }
; __device__ __forceinline__ float bflo(unsigned u) { return __uint_as_float(u << 16); }
; __device__ __forceinline__ float bfhi(unsigned u) { return __uint_as_float(u & 0xffff0000u); }
; __device__ __forceinline__ float frcp(float x) { return __builtin_amdgcn_rcpf(x); }
; __device__ __forceinline__ float silu(float x) { return x * frcp(1.f + fexp(-x)); }
; __device__ __forceinline__ void mem_unit(const Args& a, int l, LAS unsigned char* lds, int b, int hm, int qb) {
;     ...
; #pragma unroll
;     for (int qt = 0; qt < 2; ++qt) {
;         const float inv = frcp(ol[qt][0]);
;         const size_t row = rowbase + q0 + qt * 16 + fr;
; #pragma unroll
;         for (int dt = 0; dt < 8; ++dt) { const int d0 = dt * 16 + fq * 4;
;             const u32x2 z = *(const u32x2*)(proj + row * NCOL + CZ + 1024 + hm * 128 + d0);
;             u32x2 y; y.x = pk2(o[dt][qt][0] * inv * silu(bflo(z.x)), o[dt][qt][1] * inv * silu(bfhi(z.x))); y.y = pk2(o[dt][qt][2] * inv * silu(bflo(z.y)), o[dt][qt][3] * inv * silu(bfhi(z.y)));
;             *(u32x2*)(proj + row * NCOL + CQM + hm * 128 + d0) = y; }
;     }
; __global__ void __launch_bounds__(512) hymba_fwd(Args a) {
;     ...
;             for (int u0 = bx; u0 < 256; u0 += G) { const int u = (G == 256) ? (u0 & 7) * 32 + (u0 >> 3) : u0;
;                 mem_unit(a, l, lds, u >> 5, (u >> 3) & 3, u & 7); }
	v_add_f32_e32 v20, 1.0, v20
	v_rcp_f32_e32 v25, v20
	v_lshlrev_b32_e32 v20, 16, v21
	v_and_b32_e32 v21, 0xffff0000, v21
	v_pk_mul_f32 v[22:23], v[24:25], v[22:23]
	s_nop 0
	v_pk_mul_f32 v[16:17], v[16:17], v[22:23]
	s_nop 0
	v_cvt_pk_bf16_f32 v16, v16, v17
	v_mul_f32_e32 v17, 0xbfb8aa3b, v20
	v_exp_f32_e32 v17, v17
	s_nop 0
	v_add_f32_e32 v17, 1.0, v17
	v_rcp_f32_e32 v22, v17
	v_mul_f32_e32 v17, 0xbfb8aa3b, v21
	v_exp_f32_e32 v17, v17
	s_nop 0
	v_add_f32_e32 v17, 1.0, v17
	v_rcp_f32_e32 v23, v17
	s_nop 0
	v_pk_mul_f32 v[20:21], v[22:23], v[20:21]
	s_nop 0
	v_pk_mul_f32 v[18:19], v[18:19], v[20:21]
	s_nop 0
	v_cvt_pk_bf16_f32 v17, v18, v19
	v_mov_b64_e32 v[238:239], v[16:17]
	global_store_dwordx4 v[28:29], v[236:239], off offset:2112 sc1
	v_mov_b64_e32 v[16:17], v[224:225]
	v_lshlrev_b32_e32 v18, 16, v16
	v_and_b32_e32 v19, 0xffff0000, v16
	v_mul_f32_e32 v16, 0xbfb8aa3b, v18
	v_exp_f32_e32 v16, v16
	s_nop 0
	v_add_f32_e32 v16, 1.0, v16
	v_rcp_f32_e32 v20, v16
	v_mul_f32_e32 v16, 0xbfb8aa3b, v19
	v_exp_f32_e32 v16, v16
	s_nop 0
	v_add_f32_e32 v16, 1.0, v16
	v_rcp_f32_e32 v21, v16
	v_lshlrev_b32_e32 v16, 16, v17
	v_and_b32_e32 v17, 0xffff0000, v17
	v_pk_mul_f32 v[18:19], v[20:21], v[18:19]
	s_nop 0
	v_pk_mul_f32 v[12:13], v[12:13], v[18:19]
	s_nop 0
	v_cvt_pk_bf16_f32 v12, v12, v13
	v_mul_f32_e32 v13, 0xbfb8aa3b, v16
	v_exp_f32_e32 v13, v13
	s_nop 0
	v_add_f32_e32 v13, 1.0, v13
	v_rcp_f32_e32 v18, v13
	v_mul_f32_e32 v13, 0xbfb8aa3b, v17
	v_exp_f32_e32 v13, v13
	s_nop 0
	v_add_f32_e32 v13, 1.0, v13
	v_rcp_f32_e32 v19, v13
	s_nop 0
	v_pk_mul_f32 v[16:17], v[18:19], v[16:17]
	s_nop 0
	v_pk_mul_f32 v[14:15], v[14:15], v[16:17]
	s_nop 0
	v_cvt_pk_bf16_f32 v13, v14, v15
	v_mov_b64_e32 v[240:241], v[12:13]
	v_mov_b64_e32 v[12:13], v[226:227]
	v_lshlrev_b32_e32 v14, 16, v12
	v_and_b32_e32 v15, 0xffff0000, v12
	v_mul_f32_e32 v12, 0xbfb8aa3b, v14
	v_exp_f32_e32 v12, v12
	s_nop 0
	v_add_f32_e32 v12, 1.0, v12
	v_rcp_f32_e32 v16, v12
	v_mul_f32_e32 v12, 0xbfb8aa3b, v15
	v_exp_f32_e32 v12, v12
	s_nop 0
	v_add_f32_e32 v12, 1.0, v12
	v_rcp_f32_e32 v17, v12
	v_lshlrev_b32_e32 v12, 16, v13
	v_and_b32_e32 v13, 0xffff0000, v13
	v_pk_mul_f32 v[14:15], v[16:17], v[14:15]
	s_nop 0
	v_pk_mul_f32 v[8:9], v[8:9], v[14:15]
	s_nop 0
	v_cvt_pk_bf16_f32 v8, v8, v9
	v_mul_f32_e32 v9, 0xbfb8aa3b, v12
	v_exp_f32_e32 v9, v9
	s_nop 0
	v_add_f32_e32 v9, 1.0, v9
	v_rcp_f32_e32 v14, v9
	v_mul_f32_e32 v9, 0xbfb8aa3b, v13
	v_exp_f32_e32 v9, v9
	s_nop 0
	v_add_f32_e32 v9, 1.0, v9
	v_rcp_f32_e32 v15, v9
	s_nop 0
	v_pk_mul_f32 v[12:13], v[14:15], v[12:13]
	s_nop 0
	v_pk_mul_f32 v[10:11], v[10:11], v[12:13]
	s_nop 0
	v_cvt_pk_bf16_f32 v9, v10, v11
	v_mov_b64_e32 v[242:243], v[8:9]
	global_store_dwordx4 v[28:29], v[240:243], off offset:2176 sc1
	v_mov_b64_e32 v[8:9], v[228:229]
	v_lshlrev_b32_e32 v10, 16, v8
	v_and_b32_e32 v11, 0xffff0000, v8
	v_mul_f32_e32 v8, 0xbfb8aa3b, v10
	v_exp_f32_e32 v8, v8
	s_nop 0
	v_add_f32_e32 v8, 1.0, v8
	v_rcp_f32_e32 v12, v8
	v_mul_f32_e32 v8, 0xbfb8aa3b, v11
	v_exp_f32_e32 v8, v8
	s_nop 0
	v_add_f32_e32 v8, 1.0, v8
	v_rcp_f32_e32 v13, v8
	v_lshlrev_b32_e32 v8, 16, v9
	v_and_b32_e32 v9, 0xffff0000, v9
	v_pk_mul_f32 v[10:11], v[12:13], v[10:11]
	s_nop 0
	v_pk_mul_f32 v[4:5], v[4:5], v[10:11]
	s_nop 0
	v_cvt_pk_bf16_f32 v4, v4, v5
	v_mul_f32_e32 v5, 0xbfb8aa3b, v8
	v_exp_f32_e32 v5, v5
	s_nop 0
	v_add_f32_e32 v5, 1.0, v5
	v_rcp_f32_e32 v10, v5
	v_mul_f32_e32 v5, 0xbfb8aa3b, v9
	v_exp_f32_e32 v5, v5
	s_nop 0
	v_add_f32_e32 v5, 1.0, v5
	v_rcp_f32_e32 v11, v5
	s_nop 0
	v_pk_mul_f32 v[8:9], v[10:11], v[8:9]
	s_nop 0
	v_pk_mul_f32 v[6:7], v[6:7], v[8:9]
	s_nop 0
	v_cvt_pk_bf16_f32 v5, v6, v7
	v_mov_b64_e32 v[180:181], v[4:5]
	v_mov_b64_e32 v[4:5], v[230:231]
	v_lshlrev_b32_e32 v6, 16, v4
	v_and_b32_e32 v7, 0xffff0000, v4
	v_mul_f32_e32 v4, 0xbfb8aa3b, v6
	v_exp_f32_e32 v4, v4
	s_nop 0
	v_add_f32_e32 v4, 1.0, v4
	v_rcp_f32_e32 v8, v4
	v_mul_f32_e32 v4, 0xbfb8aa3b, v7
	v_exp_f32_e32 v4, v4
	s_nop 0
	v_add_f32_e32 v4, 1.0, v4
	v_rcp_f32_e32 v9, v4
	v_lshlrev_b32_e32 v4, 16, v5
	v_and_b32_e32 v5, 0xffff0000, v5
	v_pk_mul_f32 v[6:7], v[8:9], v[6:7]
	s_nop 0
	v_pk_mul_f32 v[0:1], v[0:1], v[6:7]
	s_nop 0
	v_cvt_pk_bf16_f32 v0, v0, v1
	v_mul_f32_e32 v1, 0xbfb8aa3b, v4
	v_exp_f32_e32 v1, v1
	s_nop 0
	v_add_f32_e32 v1, 1.0, v1
	v_rcp_f32_e32 v6, v1
	v_mul_f32_e32 v1, 0xbfb8aa3b, v5
	v_exp_f32_e32 v1, v1
	s_nop 0
	v_add_f32_e32 v1, 1.0, v1
	v_rcp_f32_e32 v7, v1
	s_nop 0
	v_pk_mul_f32 v[4:5], v[6:7], v[4:5]
	s_nop 0
	v_pk_mul_f32 v[2:3], v[2:3], v[4:5]
	s_nop 0
	v_cvt_pk_bf16_f32 v1, v2, v3
	v_mov_b64_e32 v[182:183], v[0:1]
	global_store_dwordx4 v[28:29], v[180:183], off offset:2240 sc1
	s_cbranch_scc0 .LBB0_519

; __device__ __forceinline__ unsigned pk2(float lo, float hi) { f32x2_t v = {lo, hi}; bf16x2_t b = __builtin_convertvector(v, bf16x2_t); return __builtin_bit_cast(unsigned, b); }
; __device__ __forceinline__ float bflo(unsigned u) { return __uint_as_float(u << 16); }
; __device__ __forceinline__ float bfhi(unsigned u) { return __uint_as_float(u & 0xffff0000u); }
; __device__ __forceinline__ float frcp(float x) { return __builtin_amdgcn_rcpf(x); }
; __device__ __forceinline__ float silu(float x) { return x * frcp(1.f + fexp(-x)); }
; __device__ __forceinline__ void moba_unit(const Args& a, int l, LAS unsigned char* lds, int b, int h, int qb) {
;     ...
; #pragma unroll
;     for (int qt = 0; qt < 2; ++qt) {
;         const float inv = frcp(ol[qt][0]);
;         const size_t row = rowbase + qrow[qt] + fr;
; #pragma unroll
;         for (int dt = 0; dt < 4; ++dt) { const int d0 = dt * 16 + fq * 4;
;             const u32x2 z = zq[qt][dt];
;             u32x2 y; y.x = pk2(o[dt][qt][0] * inv * silu(bflo(z.x)), o[dt][qt][1] * inv * silu(bfhi(z.x))); y.y = pk2(o[dt][qt][2] * inv * silu(bflo(z.y)), o[dt][qt][3] * inv * silu(bfhi(z.y)));
;             *(u32x2*)(proj + row * NCOL + CQA + h * 64 + d0) = y; }
;     }
.LBB0_543:
	s_waitcnt vmcnt(7)
	v_lshlrev_b32_e32 v4, 16, v182
	v_mul_f32_e32 v1, 0xbfb8aa3b, v4
	v_exp_f32_e32 v1, v1
	v_rcp_f32_e32 v0, v8
	v_and_b32_e32 v5, 0xffff0000, v182
	v_lshl_add_u64 v[2:3], s[44:45], 0, v[142:143]
	v_add_f32_e32 v1, 1.0, v1
	v_rcp_f32_e32 v6, v1
	v_pk_mul_f32 v[8:9], v[92:93], v[0:1] op_sel_hi:[1,0]
	v_mul_f32_e32 v1, 0xbfb8aa3b, v5
	v_exp_f32_e32 v1, v1
	v_lshlrev_b32_e32 v144, 2, v170
	v_lshl_add_u64 v[2:3], v[2:3], 0, v[144:145]
	s_add_i32 s18, s18, s3
	v_add_f32_e32 v1, 1.0, v1
	v_rcp_f32_e32 v7, v1
	s_cmpk_gt_i32 s18, 0x1ff
	v_pk_mul_f32 v[4:5], v[6:7], v[4:5]
	v_lshlrev_b32_e32 v6, 16, v183
	v_mul_f32_e32 v1, 0xbfb8aa3b, v6
	v_exp_f32_e32 v1, v1
	v_and_b32_e32 v7, 0xffff0000, v183
	v_pk_mul_f32 v[4:5], v[4:5], v[8:9]
	v_add_f32_e32 v1, 1.0, v1
	v_rcp_f32_e32 v8, v1
	v_pk_mul_f32 v[10:11], v[94:95], v[0:1] op_sel_hi:[1,0]
	v_mul_f32_e32 v1, 0xbfb8aa3b, v7
	v_exp_f32_e32 v1, v1
	v_cvt_pk_bf16_f32 v4, v4, v5
	v_add_f32_e32 v1, 1.0, v1
	v_rcp_f32_e32 v9, v1
	s_nop 0
	v_pk_mul_f32 v[6:7], v[8:9], v[6:7]
	s_nop 0
	v_pk_mul_f32 v[6:7], v[6:7], v[10:11]
	s_nop 0
	v_cvt_pk_bf16_f32 v5, v6, v7
	v_mov_b32_e32 v12, v4
	v_mov_b32_e32 v13, v5
	s_waitcnt vmcnt(6)
	v_lshlrev_b32_e32 v4, 16, v174
	v_mul_f32_e32 v1, 0xbfb8aa3b, v4
	v_exp_f32_e32 v1, v1
	v_and_b32_e32 v5, 0xffff0000, v174
	v_add_f32_e32 v1, 1.0, v1
	v_rcp_f32_e32 v6, v1
	v_pk_mul_f32 v[8:9], v[88:89], v[0:1] op_sel_hi:[1,0]
	v_mul_f32_e32 v1, 0xbfb8aa3b, v5
	v_exp_f32_e32 v1, v1
	s_nop 0
	v_add_f32_e32 v1, 1.0, v1
	v_rcp_f32_e32 v7, v1
	s_nop 0
	v_pk_mul_f32 v[4:5], v[6:7], v[4:5]
	v_lshlrev_b32_e32 v6, 16, v175
	v_mul_f32_e32 v1, 0xbfb8aa3b, v6
	v_exp_f32_e32 v1, v1
	v_and_b32_e32 v7, 0xffff0000, v175
	v_pk_mul_f32 v[4:5], v[4:5], v[8:9]
	v_add_f32_e32 v1, 1.0, v1
	v_rcp_f32_e32 v8, v1
	v_pk_mul_f32 v[10:11], v[90:91], v[0:1] op_sel_hi:[1,0]
	v_mul_f32_e32 v1, 0xbfb8aa3b, v7
	v_exp_f32_e32 v1, v1
	v_cvt_pk_bf16_f32 v4, v4, v5
	v_add_f32_e32 v1, 1.0, v1
	v_rcp_f32_e32 v9, v1
	s_nop 0
	v_pk_mul_f32 v[6:7], v[8:9], v[6:7]
	s_nop 0
	v_pk_mul_f32 v[6:7], v[6:7], v[10:11]
	s_nop 0
	v_cvt_pk_bf16_f32 v5, v6, v7
	v_mov_b32_e32 v14, v4
	v_mov_b32_e32 v15, v5
	global_store_dwordx4 v[2:3], v[12:15], off sc1
	s_waitcnt vmcnt(6)
	v_lshlrev_b32_e32 v4, 16, v172
	v_mul_f32_e32 v1, 0xbfb8aa3b, v4
	v_exp_f32_e32 v1, v1
	v_and_b32_e32 v5, 0xffff0000, v172
	v_add_f32_e32 v1, 1.0, v1
	v_rcp_f32_e32 v6, v1
	v_pk_mul_f32 v[8:9], v[100:101], v[0:1] op_sel_hi:[1,0]
	v_mul_f32_e32 v1, 0xbfb8aa3b, v5
	v_exp_f32_e32 v1, v1
	s_nop 0
	v_add_f32_e32 v1, 1.0, v1
	v_rcp_f32_e32 v7, v1
	s_nop 0
	v_pk_mul_f32 v[4:5], v[6:7], v[4:5]
	v_lshlrev_b32_e32 v6, 16, v173
	v_mul_f32_e32 v1, 0xbfb8aa3b, v6
	v_exp_f32_e32 v1, v1
	v_and_b32_e32 v7, 0xffff0000, v173
	v_pk_mul_f32 v[4:5], v[4:5], v[8:9]
	v_add_f32_e32 v1, 1.0, v1
	v_rcp_f32_e32 v8, v1
	v_pk_mul_f32 v[10:11], v[102:103], v[0:1] op_sel_hi:[1,0]
	v_mul_f32_e32 v1, 0xbfb8aa3b, v7
	v_exp_f32_e32 v1, v1
	v_cvt_pk_bf16_f32 v4, v4, v5
	v_add_f32_e32 v1, 1.0, v1
	v_rcp_f32_e32 v9, v1
	s_nop 0
	v_pk_mul_f32 v[6:7], v[8:9], v[6:7]
	s_nop 0
	v_pk_mul_f32 v[6:7], v[6:7], v[10:11]
	s_nop 0
	v_cvt_pk_bf16_f32 v5, v6, v7
	v_mov_b32_e32 v20, v4
	v_mov_b32_e32 v21, v5
	s_waitcnt vmcnt(5)
	v_lshlrev_b32_e32 v4, 16, v168
	v_mul_f32_e32 v1, 0xbfb8aa3b, v4
	v_exp_f32_e32 v1, v1
	v_and_b32_e32 v5, 0xffff0000, v168
	v_add_f32_e32 v1, 1.0, v1
	v_rcp_f32_e32 v6, v1
	v_pk_mul_f32 v[8:9], v[112:113], v[0:1] op_sel_hi:[1,0]
	v_mul_f32_e32 v1, 0xbfb8aa3b, v5
	v_exp_f32_e32 v1, v1
	s_nop 0
	v_add_f32_e32 v1, 1.0, v1
	v_rcp_f32_e32 v7, v1
	s_nop 0
	v_pk_mul_f32 v[4:5], v[6:7], v[4:5]
	s_nop 0
	v_pk_mul_f32 v[4:5], v[4:5], v[8:9]
	v_lshlrev_b32_e32 v6, 16, v169
	v_and_b32_e32 v7, 0xffff0000, v169
	v_cvt_pk_bf16_f32 v4, v4, v5
	v_mul_f32_e32 v1, 0xbfb8aa3b, v6
	v_mul_f32_e32 v5, 0xbfb8aa3b, v7
	v_exp_f32_e32 v1, v1
	v_exp_f32_e32 v5, v5
	v_add_f32_e32 v1, 1.0, v1
	v_add_f32_e32 v5, 1.0, v5
	v_rcp_f32_e32 v8, v1
	v_rcp_f32_e32 v9, v5
	v_pk_mul_f32 v[0:1], v[114:115], v[0:1] op_sel_hi:[1,0]
	v_pk_mul_f32 v[6:7], v[8:9], v[6:7]
	s_nop 0
	v_pk_mul_f32 v[0:1], v[6:7], v[0:1]
	s_nop 0
	v_cvt_pk_bf16_f32 v5, v0, v1
	v_mov_b32_e32 v22, v4
	v_mov_b32_e32 v23, v5
	global_store_dwordx4 v[2:3], v[20:23], off offset:64 sc1
	s_waitcnt vmcnt(5)
; __device__ __forceinline__ unsigned pk2(float lo, float hi) { f32x2_t v = {lo, hi}; bf16x2_t b = __builtin_convertvector(v, bf16x2_t); return __builtin_bit_cast(unsigned, b); }
; __device__ __forceinline__ float bflo(unsigned u) { return __uint_as_float(u << 16); }
; __device__ __forceinline__ float bfhi(unsigned u) { return __uint_as_float(u & 0xffff0000u); }
; __device__ __forceinline__ float frcp(float x) { return __builtin_amdgcn_rcpf(x); }
; __device__ __forceinline__ float silu(float x) { return x * frcp(1.f + fexp(-x)); }
; __device__ __forceinline__ void moba_unit(const Args& a, int l, LAS unsigned char* lds, int b, int h, int qb) {
;     ...
; #pragma unroll
;     for (int qt = 0; qt < 2; ++qt) {
;         const float inv = frcp(ol[qt][0]);
;         const size_t row = rowbase + qrow[qt] + fr;
; #pragma unroll
;         for (int dt = 0; dt < 4; ++dt) { const int d0 = dt * 16 + fq * 4;
;             const u32x2 z = zq[qt][dt];
;             u32x2 y; y.x = pk2(o[dt][qt][0] * inv * silu(bflo(z.x)), o[dt][qt][1] * inv * silu(bfhi(z.x))); y.y = pk2(o[dt][qt][2] * inv * silu(bflo(z.y)), o[dt][qt][3] * inv * silu(bfhi(z.y)));
;             *(u32x2*)(proj + row * NCOL + CQA + h * 64 + d0) = y; }
;     }
;     __syncthreads();
	v_lshlrev_b32_e32 v4, 16, v166
	v_mul_f32_e32 v1, 0xbfb8aa3b, v4
	v_exp_f32_e32 v1, v1
	v_rcp_f32_e32 v0, v96
	v_and_b32_e32 v5, 0xffff0000, v166
	v_lshl_add_u64 v[2:3], s[44:45], 0, v[140:141]
	v_add_f32_e32 v1, 1.0, v1
	v_rcp_f32_e32 v6, v1
	v_pk_mul_f32 v[8:9], v[104:105], v[0:1] op_sel_hi:[1,0]
	v_mul_f32_e32 v1, 0xbfb8aa3b, v5
	v_exp_f32_e32 v1, v1
	v_lshl_add_u64 v[2:3], v[2:3], 0, v[144:145]
	v_add_f32_e32 v1, 1.0, v1
	v_rcp_f32_e32 v7, v1
	s_nop 0
	v_pk_mul_f32 v[4:5], v[6:7], v[4:5]
	v_lshlrev_b32_e32 v6, 16, v167
	v_mul_f32_e32 v1, 0xbfb8aa3b, v6
	v_exp_f32_e32 v1, v1
	v_and_b32_e32 v7, 0xffff0000, v167
	v_pk_mul_f32 v[4:5], v[4:5], v[8:9]
	v_add_f32_e32 v1, 1.0, v1
	v_rcp_f32_e32 v8, v1
	v_pk_mul_f32 v[10:11], v[106:107], v[0:1] op_sel_hi:[1,0]
	v_mul_f32_e32 v1, 0xbfb8aa3b, v7
	v_exp_f32_e32 v1, v1
	v_cvt_pk_bf16_f32 v4, v4, v5
	v_add_f32_e32 v1, 1.0, v1
	v_rcp_f32_e32 v9, v1
	s_nop 0
	v_pk_mul_f32 v[6:7], v[8:9], v[6:7]
	s_nop 0
	v_pk_mul_f32 v[6:7], v[6:7], v[10:11]
	s_nop 0
	v_cvt_pk_bf16_f32 v5, v6, v7
	v_mov_b32_e32 v24, v4
	v_mov_b32_e32 v25, v5
	s_waitcnt vmcnt(4)
	v_lshlrev_b32_e32 v4, 16, v164
	v_mul_f32_e32 v1, 0xbfb8aa3b, v4
	v_exp_f32_e32 v1, v1
	v_and_b32_e32 v5, 0xffff0000, v164
	v_add_f32_e32 v1, 1.0, v1
	v_rcp_f32_e32 v6, v1
	v_pk_mul_f32 v[8:9], v[16:17], v[0:1] op_sel_hi:[1,0]
	v_mul_f32_e32 v1, 0xbfb8aa3b, v5
	v_exp_f32_e32 v1, v1
	s_nop 0
	v_add_f32_e32 v1, 1.0, v1
	v_rcp_f32_e32 v7, v1
	s_nop 0
	v_pk_mul_f32 v[4:5], v[6:7], v[4:5]
	v_lshlrev_b32_e32 v6, 16, v165
	v_mul_f32_e32 v1, 0xbfb8aa3b, v6
	v_exp_f32_e32 v1, v1
	v_and_b32_e32 v7, 0xffff0000, v165
	v_pk_mul_f32 v[4:5], v[4:5], v[8:9]
	v_add_f32_e32 v1, 1.0, v1
	v_rcp_f32_e32 v8, v1
	v_pk_mul_f32 v[10:11], v[18:19], v[0:1] op_sel_hi:[1,0]
	v_mul_f32_e32 v1, 0xbfb8aa3b, v7
	v_exp_f32_e32 v1, v1
	v_cvt_pk_bf16_f32 v4, v4, v5
	v_add_f32_e32 v1, 1.0, v1
	v_rcp_f32_e32 v9, v1
	s_nop 0
	v_pk_mul_f32 v[6:7], v[8:9], v[6:7]
	s_nop 0
	v_pk_mul_f32 v[6:7], v[6:7], v[10:11]
	s_nop 0
	v_cvt_pk_bf16_f32 v5, v6, v7
	v_mov_b32_e32 v26, v4
	v_mov_b32_e32 v27, v5
	global_store_dwordx4 v[2:3], v[24:27], off sc1
	s_waitcnt vmcnt(4)
	v_lshlrev_b32_e32 v4, 16, v162
	v_mul_f32_e32 v1, 0xbfb8aa3b, v4
	v_exp_f32_e32 v1, v1
	v_and_b32_e32 v5, 0xffff0000, v162
	v_add_f32_e32 v1, 1.0, v1
	v_rcp_f32_e32 v6, v1
	v_pk_mul_f32 v[8:9], v[108:109], v[0:1] op_sel_hi:[1,0]
	v_mul_f32_e32 v1, 0xbfb8aa3b, v5
	v_exp_f32_e32 v1, v1
	s_nop 0
	v_add_f32_e32 v1, 1.0, v1
	v_rcp_f32_e32 v7, v1
	s_nop 0
	v_pk_mul_f32 v[4:5], v[6:7], v[4:5]
	v_lshlrev_b32_e32 v6, 16, v163
	v_mul_f32_e32 v1, 0xbfb8aa3b, v6
	v_exp_f32_e32 v1, v1
	v_and_b32_e32 v7, 0xffff0000, v163
	v_pk_mul_f32 v[4:5], v[4:5], v[8:9]
	v_add_f32_e32 v1, 1.0, v1
	v_rcp_f32_e32 v8, v1
	v_pk_mul_f32 v[10:11], v[110:111], v[0:1] op_sel_hi:[1,0]
	v_mul_f32_e32 v1, 0xbfb8aa3b, v7
	v_exp_f32_e32 v1, v1
	v_cvt_pk_bf16_f32 v4, v4, v5
	v_add_f32_e32 v1, 1.0, v1
	v_rcp_f32_e32 v9, v1
	s_nop 0
	v_pk_mul_f32 v[6:7], v[8:9], v[6:7]
	s_nop 0
	v_pk_mul_f32 v[6:7], v[6:7], v[10:11]
	s_nop 0
	v_cvt_pk_bf16_f32 v5, v6, v7
	v_mov_b32_e32 v28, v4
	v_mov_b32_e32 v29, v5
	s_waitcnt vmcnt(3)
	v_lshlrev_b32_e32 v4, 16, v160
	v_mul_f32_e32 v1, 0xbfb8aa3b, v4
	v_exp_f32_e32 v1, v1
	v_and_b32_e32 v5, 0xffff0000, v160
	v_add_f32_e32 v1, 1.0, v1
	v_rcp_f32_e32 v6, v1
	v_pk_mul_f32 v[8:9], v[132:133], v[0:1] op_sel_hi:[1,0]
	v_mul_f32_e32 v1, 0xbfb8aa3b, v5
	v_exp_f32_e32 v1, v1
	s_nop 0
	v_add_f32_e32 v1, 1.0, v1
	v_rcp_f32_e32 v7, v1
	s_nop 0
	v_pk_mul_f32 v[4:5], v[6:7], v[4:5]
	s_nop 0
	v_pk_mul_f32 v[4:5], v[4:5], v[8:9]
	v_lshlrev_b32_e32 v6, 16, v161
	v_and_b32_e32 v7, 0xffff0000, v161
	v_cvt_pk_bf16_f32 v4, v4, v5
	v_mul_f32_e32 v1, 0xbfb8aa3b, v6
	v_mul_f32_e32 v5, 0xbfb8aa3b, v7
	v_exp_f32_e32 v1, v1
	v_exp_f32_e32 v5, v5
	v_add_f32_e32 v1, 1.0, v1
	v_add_f32_e32 v5, 1.0, v5
	v_rcp_f32_e32 v8, v1
	v_rcp_f32_e32 v9, v5
	v_pk_mul_f32 v[0:1], v[134:135], v[0:1] op_sel_hi:[1,0]
	v_pk_mul_f32 v[6:7], v[8:9], v[6:7]
	s_nop 0
	v_pk_mul_f32 v[0:1], v[6:7], v[0:1]
	s_nop 0
	v_cvt_pk_bf16_f32 v5, v0, v1
	v_mov_b32_e32 v30, v4
	v_mov_b32_e32 v31, v5
	global_store_dwordx4 v[2:3], v[28:31], off offset:64 sc1
	s_waitcnt lgkmcnt(0)
	s_barrier
	s_cbranch_scc1 .LBB0_517

; #define LAS __attribute__((address_space(3)))
; __device__ __forceinline__ unsigned pk2(float lo, float hi) { f32x2_t v = {lo, hi}; bf16x2_t b = __builtin_convertvector(v, bf16x2_t); return __builtin_bit_cast(unsigned, b); }
; __device__ __forceinline__ float bflo(unsigned u) { return __uint_as_float(u << 16); }
; __device__ __forceinline__ float bfhi(unsigned u) { return __uint_as_float(u & 0xffff0000u); }
; __device__ __forceinline__ float frsq(float x) { return __builtin_amdgcn_rsqf(x); }
; __device__ __forceinline__ float silu(float x) { return x * frcp(1.f + fexp(-x)); }
; #define BAR_LDS() do { asm volatile("s_waitcnt lgkmcnt(0)" ::: "memory"); __builtin_amdgcn_s_barrier(); asm volatile("" ::: "memory"); } while (0)
; __device__ __forceinline__ void hgrn_stage3_unit(const Args& a, int l, LAS unsigned char* lds, int tid, int u, const HIn& in, HIn& nxt, int unext) {
;     ...
;     ss += __shfl_xor(ss, 16); ss += __shfl_xor(ss, 32);
;     if (fq == 0) SSQ[vh * 64 + tt * 16 + fr] = ss;
;     BAR_LDS();
;     const float tot = SSQ[tt * 16 + fr] + SSQ[64 + tt * 16 + fr];
;     const float r = frsq(tot * (1.f / 128.f) + EPS);
; #pragma unroll
;     for (int v = 0; v < 4; ++v) { const int v0 = (vh * 4 + v) * 16 + fq * 4;
;         const f32x4 g = *(const LAS f32x4*)((const LAS float*)(lds + 106496 + 2048) + v0);
;         const u32x2 z = zz[v];
;         u32x2 y; y.x = pk2(o[v][0] * r * g.x * silu(bflo(z.x)), o[v][1] * r * g.y * silu(bfhi(z.x))); y.y = pk2(o[v][2] * r * g.z * silu(bflo(z.y)), o[v][3] * r * g.w * silu(bfhi(z.y)));
;         *(u32x2*)(proj + row * NCOL + CQH + hh * 128 + v0) = y; }
;     BAR_LDS();
.LBB0_643:
	s_or_b64 exec, exec, s[14:15]
	s_waitcnt lgkmcnt(0)
	s_barrier
	v_lshl_add_u32 v40, s4, 2, v196
	s_waitcnt lgkmcnt(0)
	ds_read2st64_b32 v[40:41], v40 offset1:1
	s_waitcnt vmcnt(9)
	v_lshlrev_b32_e32 v54, 16, v132
	v_and_b32_e32 v55, 0xffff0000, v132
	v_mul_f32_e32 v42, 0xbfb8aa3b, v54
	v_exp_f32_e32 v46, v42
	v_mul_f32_e32 v42, 0xbfb8aa3b, v55
	v_exp_f32_e32 v47, v42
	v_or_b32_e32 v50, s40, v122
	s_waitcnt lgkmcnt(0)
	v_add_f32_e32 v40, v40, v41
	v_lshl_add_u32 v41, v50, 2, 0
	v_fmamk_f32 v40, v40, 0x3c000000, v186
	v_add_u32_e32 v41, 0x1a800, v41
	v_add_f32_e32 v46, 1.0, v46
	v_rsq_f32_e32 v40, v40
	ds_read_b128 v[42:45], v41
	v_rcp_f32_e32 v56, v46
	v_add_f32_e32 v46, 1.0, v47
	v_rcp_f32_e32 v57, v46
	v_pk_mul_f32 v[36:37], v[36:37], v[40:41] op_sel_hi:[1,0]
	ds_read_b128 v[46:49], v41 offset:64
	s_waitcnt lgkmcnt(1)
	v_pk_mul_f32 v[36:37], v[42:43], v[36:37]
	v_pk_mul_f32 v[42:43], v[56:57], v[54:55]
	v_lshlrev_b32_e32 v54, 16, v133
	v_and_b32_e32 v55, 0xffff0000, v133
	v_mul_f32_e32 v51, 0xbfb8aa3b, v54
	v_mul_f32_e32 v56, 0xbfb8aa3b, v55
	v_exp_f32_e32 v51, v51
	v_exp_f32_e32 v56, v56
	v_pk_mul_f32 v[36:37], v[42:43], v[36:37]
	v_pk_mul_f32 v[38:39], v[38:39], v[40:41] op_sel_hi:[1,0]
	v_add_f32_e32 v42, 1.0, v51
	v_add_f32_e32 v43, 1.0, v56
	v_rcp_f32_e32 v42, v42
	v_rcp_f32_e32 v43, v43
	v_pk_mul_f32 v[38:39], v[44:45], v[38:39]
	v_cvt_pk_bf16_f32 v36, v36, v37
	s_lshl_b32 s4, s9, 7
	v_pk_mul_f32 v[42:43], v[42:43], v[54:55]
	s_lshl_b32 s6, s4, 1
	v_pk_mul_f32 v[38:39], v[42:43], v[38:39]
	v_lshl_add_u64 v[52:53], v[134:135], 0, s[6:7]
	v_cvt_pk_bf16_f32 v37, v38, v39
	s_waitcnt vmcnt(8)
	v_lshlrev_b32_e32 v38, 16, v130
	v_and_b32_e32 v39, 0xffff0000, v130
	v_mul_f32_e32 v42, 0xbfb8aa3b, v38
	v_exp_f32_e32 v44, v42
	v_mul_f32_e32 v42, 0xbfb8aa3b, v39
	v_exp_f32_e32 v45, v42
	v_ashrrev_i32_e32 v51, 31, v50
	v_add_f32_e32 v44, 1.0, v44
	v_rcp_f32_e32 v44, v44
	v_add_f32_e32 v45, 1.0, v45
	v_rcp_f32_e32 v45, v45
	v_lshlrev_b32_e32 v58, 1, v122
	v_mov_b32_e32 v59, 0
	v_or_b32_e32 v58, s40, v58
	v_lshl_add_u64 v[42:43], v[58:59], 1, v[52:53]
	v_mov_b64_e32 v[60:61], v[36:37]
	v_pk_mul_f32 v[32:33], v[32:33], v[40:41] op_sel_hi:[1,0]
	v_pk_mul_f32 v[36:37], v[44:45], v[38:39]
	v_lshlrev_b32_e32 v38, 16, v131
	v_and_b32_e32 v39, 0xffff0000, v131
	v_mul_f32_e32 v44, 0xbfb8aa3b, v38
	v_mul_f32_e32 v45, 0xbfb8aa3b, v39
	v_exp_f32_e32 v44, v44
	v_exp_f32_e32 v45, v45
	s_waitcnt lgkmcnt(0)
	v_pk_mul_f32 v[32:33], v[46:47], v[32:33]
	v_pk_mul_f32 v[34:35], v[34:35], v[40:41] op_sel_hi:[1,0]
	v_pk_mul_f32 v[32:33], v[36:37], v[32:33]
	v_add_f32_e32 v36, 1.0, v44
	v_add_f32_e32 v37, 1.0, v45
	v_rcp_f32_e32 v36, v36
	v_rcp_f32_e32 v37, v37
	v_pk_mul_f32 v[34:35], v[48:49], v[34:35]
	v_cvt_pk_bf16_f32 v32, v32, v33
	s_waitcnt vmcnt(7)
	v_lshlrev_b32_e32 v44, 16, v128
	v_pk_mul_f32 v[36:37], v[36:37], v[38:39]
	v_and_b32_e32 v45, 0xffff0000, v128
	v_pk_mul_f32 v[34:35], v[36:37], v[34:35]
	v_pk_mul_f32 v[28:29], v[28:29], v[40:41] op_sel_hi:[1,0]
	v_cvt_pk_bf16_f32 v33, v34, v35
	v_mov_b64_e32 v[62:63], v[32:33]
	global_store_dwordx4 v[42:43], v[60:63], off offset:1024 sc1
	v_mul_f32_e32 v32, 0xbfb8aa3b, v44
	v_exp_f32_e32 v36, v32
	v_mul_f32_e32 v32, 0xbfb8aa3b, v45
	v_exp_f32_e32 v37, v32
	ds_read_b128 v[32:35], v41 offset:128
	v_add_f32_e32 v36, 1.0, v36
	v_rcp_f32_e32 v46, v36
	v_add_f32_e32 v36, 1.0, v37
	v_rcp_f32_e32 v47, v36
	ds_read_b128 v[36:39], v41 offset:192
	s_waitcnt lgkmcnt(1)
	v_pk_mul_f32 v[28:29], v[28:29], v[32:33]
	s_waitcnt vmcnt(5)
	v_mov_b64_e32 v[74:75], v[10:11]
	v_pk_mul_f32 v[32:33], v[46:47], v[44:45]
	v_lshlrev_b32_e32 v44, 16, v129
	v_and_b32_e32 v45, 0xffff0000, v129
	v_mul_f32_e32 v41, 0xbfb8aa3b, v44
	v_mul_f32_e32 v46, 0xbfb8aa3b, v45
	v_exp_f32_e32 v41, v41
	v_exp_f32_e32 v46, v46
	v_pk_mul_f32 v[28:29], v[32:33], v[28:29]
	s_waitcnt vmcnt(4)
	v_mov_b64_e32 v[102:103], v[14:15]
	v_add_f32_e32 v32, 1.0, v41
	v_add_f32_e32 v33, 1.0, v46
	v_rcp_f32_e32 v32, v32
	v_rcp_f32_e32 v33, v33
	v_pk_mul_f32 v[30:31], v[30:31], v[40:41] op_sel_hi:[1,0]
	v_cvt_pk_bf16_f32 v28, v28, v29
	v_pk_mul_f32 v[30:31], v[30:31], v[34:35]
	v_pk_mul_f32 v[32:33], v[32:33], v[44:45]
	v_pk_mul_f32 v[24:25], v[24:25], v[40:41] op_sel_hi:[1,0]
	v_pk_mul_f32 v[30:31], v[32:33], v[30:31]
	v_lshlrev_b32_e32 v32, 16, v126
	v_and_b32_e32 v33, 0xffff0000, v126
	v_mul_f32_e32 v29, 0xbfb8aa3b, v32
	v_exp_f32_e32 v34, v29
	v_mul_f32_e32 v29, 0xbfb8aa3b, v33
	v_exp_f32_e32 v35, v29
	v_cvt_pk_bf16_f32 v29, v30, v31
	v_add_f32_e32 v30, 1.0, v34
	v_rcp_f32_e32 v30, v30
	v_add_f32_e32 v31, 1.0, v35
	v_rcp_f32_e32 v31, v31
	v_mov_b64_e32 v[64:65], v[28:29]
	s_waitcnt lgkmcnt(0)
	v_pk_mul_f32 v[24:25], v[24:25], v[36:37]
	v_pk_mul_f32 v[26:27], v[26:27], v[40:41] op_sel_hi:[1,0]
	v_pk_mul_f32 v[28:29], v[30:31], v[32:33]
	v_lshlrev_b32_e32 v30, 16, v127
	v_and_b32_e32 v31, 0xffff0000, v127
	v_mul_f32_e32 v32, 0xbfb8aa3b, v30
	v_mul_f32_e32 v33, 0xbfb8aa3b, v31
	v_exp_f32_e32 v32, v32
	v_exp_f32_e32 v33, v33
	v_pk_mul_f32 v[24:25], v[28:29], v[24:25]
	v_pk_mul_f32 v[26:27], v[26:27], v[38:39]
	v_add_f32_e32 v28, 1.0, v32
	v_add_f32_e32 v29, 1.0, v33
	v_rcp_f32_e32 v28, v28
	v_rcp_f32_e32 v29, v29
	v_cvt_pk_bf16_f32 v24, v24, v25
	s_andn2_b64 vcc, exec, s[70:71]
	v_mov_b64_e32 v[72:73], v[8:9]
	v_pk_mul_f32 v[28:29], v[28:29], v[30:31]
	v_mov_b64_e32 v[100:101], v[12:13]
	v_pk_mul_f32 v[26:27], v[28:29], v[26:27]
	s_waitcnt vmcnt(1)
	v_mov_b64_e32 v[30:31], v[22:23]
	v_cvt_pk_bf16_f32 v25, v26, v27
	v_mov_b64_e32 v[66:67], v[24:25]
	global_store_dwordx4 v[42:43], v[64:67], off offset:1088 sc1
	s_waitcnt lgkmcnt(0)
	s_barrier
	v_mov_b64_e32 v[26:27], v[18:19]
	v_mov_b64_e32 v[24:25], v[16:17]
	v_mov_b64_e32 v[28:29], v[20:21]
	s_cbranch_vccz .LBB0_679
